# v9 + the redundant first accumulator-zeroing block (128 v_mov per unit) moved to the early-exit path of the six GEMM K loops
# speedup vs baseline: 1.0080x; 1.0080x over previous
.LBB0_205:
	s_andn2_b64 vcc, exec, s[64:65]
	s_cbranch_vccnz .Lzx207
	s_add_u32 s6, s10, 0x80
	s_addc_u32 s7, s11, 0
	s_add_u32 s10, s8, 0x100
	v_mov_b32_e32 v0, 0
	s_addc_u32 s11, s9, 0
	s_mov_b32 s8, 0
	v_mov_b32_e32 v1, v0
	v_mov_b32_e32 v2, v0
	v_mov_b32_e32 v3, v0
	v_mov_b32_e32 v4, v0
	v_mov_b32_e32 v5, v0
	v_mov_b32_e32 v6, v0
	v_mov_b32_e32 v7, v0
	v_mov_b32_e32 v16, v0
	v_mov_b32_e32 v17, v0
	v_mov_b32_e32 v18, v0
	v_mov_b32_e32 v19, v0
	v_mov_b32_e32 v20, v0
	v_mov_b32_e32 v21, v0
	v_mov_b32_e32 v22, v0
	v_mov_b32_e32 v23, v0
	v_mov_b32_e32 v32, v0
	v_mov_b32_e32 v33, v0
	v_mov_b32_e32 v34, v0
	v_mov_b32_e32 v35, v0
	v_mov_b32_e32 v36, v0
	v_mov_b32_e32 v37, v0
	v_mov_b32_e32 v38, v0
	v_mov_b32_e32 v39, v0
	v_mov_b32_e32 v48, v0
	v_mov_b32_e32 v49, v0
	v_mov_b32_e32 v50, v0
	v_mov_b32_e32 v51, v0
	v_mov_b32_e32 v52, v0
	v_mov_b32_e32 v53, v0
	v_mov_b32_e32 v54, v0
	v_mov_b32_e32 v55, v0
	v_mov_b32_e32 v8, v0
	v_mov_b32_e32 v9, v0
	v_mov_b32_e32 v10, v0
	v_mov_b32_e32 v11, v0
	v_mov_b32_e32 v12, v0
	v_mov_b32_e32 v13, v0
	v_mov_b32_e32 v14, v0
	v_mov_b32_e32 v15, v0
	v_mov_b32_e32 v24, v0
	v_mov_b32_e32 v25, v0
	v_mov_b32_e32 v26, v0
	v_mov_b32_e32 v27, v0
	v_mov_b32_e32 v28, v0
	v_mov_b32_e32 v29, v0
	v_mov_b32_e32 v30, v0
	v_mov_b32_e32 v31, v0
	v_mov_b32_e32 v40, v0
	v_mov_b32_e32 v41, v0
	v_mov_b32_e32 v42, v0
	v_mov_b32_e32 v43, v0
	v_mov_b32_e32 v44, v0
	v_mov_b32_e32 v45, v0
	v_mov_b32_e32 v46, v0
	v_mov_b32_e32 v47, v0
	v_mov_b32_e32 v56, v0
	v_mov_b32_e32 v57, v0
	v_mov_b32_e32 v58, v0
	v_mov_b32_e32 v59, v0
	v_mov_b32_e32 v60, v0
	v_mov_b32_e32 v61, v0
	v_mov_b32_e32 v62, v0
	v_mov_b32_e32 v63, v0
	v_mov_b32_e32 v64, v0
	v_mov_b32_e32 v65, v0
	v_mov_b32_e32 v66, v0
	v_mov_b32_e32 v67, v0
	v_mov_b32_e32 v68, v0
	v_mov_b32_e32 v69, v0
	v_mov_b32_e32 v70, v0
	v_mov_b32_e32 v71, v0
	v_mov_b32_e32 v80, v0
	v_mov_b32_e32 v81, v0
	v_mov_b32_e32 v82, v0
	v_mov_b32_e32 v83, v0
	v_mov_b32_e32 v84, v0
	v_mov_b32_e32 v85, v0
	v_mov_b32_e32 v86, v0
	v_mov_b32_e32 v87, v0
	v_mov_b32_e32 v96, v0
	v_mov_b32_e32 v97, v0
	v_mov_b32_e32 v98, v0
	v_mov_b32_e32 v99, v0
	v_mov_b32_e32 v100, v0
	v_mov_b32_e32 v101, v0
	v_mov_b32_e32 v102, v0
	v_mov_b32_e32 v103, v0
	v_mov_b32_e32 v112, v0
	v_mov_b32_e32 v113, v0
	v_mov_b32_e32 v114, v0
	v_mov_b32_e32 v115, v0
	v_mov_b32_e32 v116, v0
	v_mov_b32_e32 v117, v0
	v_mov_b32_e32 v118, v0
	v_mov_b32_e32 v119, v0
	v_mov_b32_e32 v72, v0
	v_mov_b32_e32 v73, v0
	v_mov_b32_e32 v74, v0
	v_mov_b32_e32 v75, v0
	v_mov_b32_e32 v76, v0
	v_mov_b32_e32 v77, v0
	v_mov_b32_e32 v78, v0
	v_mov_b32_e32 v79, v0
	v_mov_b32_e32 v88, v0
	v_mov_b32_e32 v89, v0
	v_mov_b32_e32 v90, v0
	v_mov_b32_e32 v91, v0
	v_mov_b32_e32 v92, v0
	v_mov_b32_e32 v93, v0
	v_mov_b32_e32 v94, v0
	v_mov_b32_e32 v95, v0
	v_mov_b32_e32 v104, v0
	v_mov_b32_e32 v105, v0
	v_mov_b32_e32 v106, v0
	v_mov_b32_e32 v107, v0
	v_mov_b32_e32 v108, v0
	v_mov_b32_e32 v109, v0
	v_mov_b32_e32 v110, v0
	v_mov_b32_e32 v111, v0
	v_mov_b32_e32 v120, v0
	v_mov_b32_e32 v121, v0
	v_mov_b32_e32 v122, v0
	v_mov_b32_e32 v123, v0
	v_mov_b32_e32 v124, v0
	v_mov_b32_e32 v125, v0
	v_mov_b32_e32 v126, v0
	v_mov_b32_e32 v127, v0
.LBB0_207:
	ds_read_b128 v[152:155], v168
	ds_read_b128 v[156:159], v168 offset:1024
	ds_read_b128 v[172:175], v168 offset:2048
	ds_read_b128 v[176:179], v168 offset:3072
	ds_read_b128 v[180:183], v169
	ds_read_b128 v[186:189], v169 offset:1024
	ds_read_b128 v[190:193], v169 offset:2048
	ds_read_b128 v[194:197], v169 offset:3072
	s_add_i32 s12, s8, 2
	s_add_u32 s13, s6, 0x80
	s_addc_u32 s9, s7, 0
	s_cmp_eq_u32 s52, s8
	s_cselect_b32 s8, s86, s13
	s_cselect_b32 s9, s87, s9
	s_cselect_b32 s17, s89, s11
	s_cselect_b32 s16, s88, s10
	v_lshl_add_u64 v[160:161], s[6:7], 0, v[144:145]
	s_add_i32 m0, s90, 0xc000
	ds_read_b128 v[198:201], v170
	ds_read_b128 v[202:205], v170 offset:1024
	ds_read_b128 v[206:209], v170 offset:2048
	ds_read_b128 v[210:213], v170 offset:3072
	ds_read_b128 v[214:217], v170 offset:4096
	ds_read_b128 v[224:227], v170 offset:5120
	ds_read_b128 v[228:231], v170 offset:6144
	ds_read_b128 v[232:235], v170 offset:7168
	global_load_lds_dwordx4 v[160:161], off
	v_lshl_add_u64 v[160:161], s[6:7], 0, v[146:147]
	s_add_i32 m0, s90, 0xe000
	s_nop 0
	global_load_lds_dwordx4 v[160:161], off
	s_waitcnt vmcnt(8)
	s_waitcnt lgkmcnt(0)
	s_barrier
	s_setprio 1
	s_waitcnt lgkmcnt(0)
	v_mfma_f32_16x16x32_bf16 v[124:127], v[152:155], v[198:201], v[124:127]
	v_mfma_f32_16x16x32_bf16 v[120:123], v[172:175], v[198:201], v[120:123]
	v_mfma_f32_16x16x32_bf16 v[108:111], v[152:155], v[206:209], v[108:111]
	v_mfma_f32_16x16x32_bf16 v[104:107], v[172:175], v[206:209], v[104:107]
	v_mfma_f32_16x16x32_bf16 v[92:95], v[152:155], v[214:217], v[92:95]
	v_mfma_f32_16x16x32_bf16 v[88:91], v[172:175], v[214:217], v[88:91]
	v_mfma_f32_16x16x32_bf16 v[76:79], v[152:155], v[228:231], v[76:79]
	v_mfma_f32_16x16x32_bf16 v[72:75], v[172:175], v[228:231], v[72:75]
	v_mfma_f32_16x16x32_bf16 v[124:127], v[156:159], v[202:205], v[124:127]
	v_mfma_f32_16x16x32_bf16 v[120:123], v[176:179], v[202:205], v[120:123]
	v_mfma_f32_16x16x32_bf16 v[108:111], v[156:159], v[210:213], v[108:111]
	v_mfma_f32_16x16x32_bf16 v[104:107], v[176:179], v[210:213], v[104:107]
	v_mfma_f32_16x16x32_bf16 v[92:95], v[156:159], v[224:227], v[92:95]
	v_mfma_f32_16x16x32_bf16 v[88:91], v[176:179], v[224:227], v[88:91]
	v_mfma_f32_16x16x32_bf16 v[76:79], v[156:159], v[232:235], v[76:79]
	v_mfma_f32_16x16x32_bf16 v[72:75], v[176:179], v[232:235], v[72:75]
	s_setprio 0
	s_setprio 1
	v_mfma_f32_16x16x32_bf16 v[116:119], v[180:183], v[198:201], v[116:119]
	v_mfma_f32_16x16x32_bf16 v[112:115], v[190:193], v[198:201], v[112:115]
	v_mfma_f32_16x16x32_bf16 v[100:103], v[180:183], v[206:209], v[100:103]
	v_mfma_f32_16x16x32_bf16 v[96:99], v[190:193], v[206:209], v[96:99]
	v_mfma_f32_16x16x32_bf16 v[84:87], v[180:183], v[214:217], v[84:87]
	v_mfma_f32_16x16x32_bf16 v[80:83], v[190:193], v[214:217], v[80:83]
	v_mfma_f32_16x16x32_bf16 v[68:71], v[180:183], v[228:231], v[68:71]
	v_mfma_f32_16x16x32_bf16 v[64:67], v[190:193], v[228:231], v[64:67]
	v_mfma_f32_16x16x32_bf16 v[116:119], v[186:189], v[202:205], v[116:119]
	v_mfma_f32_16x16x32_bf16 v[112:115], v[194:197], v[202:205], v[112:115]
	v_mfma_f32_16x16x32_bf16 v[100:103], v[186:189], v[210:213], v[100:103]
	v_mfma_f32_16x16x32_bf16 v[96:99], v[194:197], v[210:213], v[96:99]
	v_mfma_f32_16x16x32_bf16 v[84:87], v[186:189], v[224:227], v[84:87]
	v_mfma_f32_16x16x32_bf16 v[80:83], v[194:197], v[224:227], v[80:83]
	v_mfma_f32_16x16x32_bf16 v[68:71], v[186:189], v[232:235], v[68:71]
	v_mfma_f32_16x16x32_bf16 v[64:67], v[194:197], v[232:235], v[64:67]
	s_setprio 0
	s_barrier
	s_add_i32 s13, s37, s31
	v_lshl_add_u64 v[160:161], s[16:17], 0, v[130:131]
	s_mov_b32 m0, s13
	ds_read_b128 v[198:201], v170 offset:16384
	ds_read_b128 v[202:205], v170 offset:17408
	ds_read_b128 v[206:209], v170 offset:18432
	ds_read_b128 v[210:213], v170 offset:19456
	ds_read_b128 v[214:217], v170 offset:20480
	ds_read_b128 v[224:227], v170 offset:21504
	ds_read_b128 v[228:231], v170 offset:22528
	ds_read_b128 v[232:235], v170 offset:23552
	global_load_lds_dwordx4 v[160:161], off
	s_add_i32 m0, s13, 0x2000
	v_lshl_add_u64 v[236:237], s[16:17], 0, v[134:135]
	s_add_u32 s16, s16, s74
	s_addc_u32 s17, s17, s75
	s_add_i32 s13, s38, s31
	global_load_lds_dwordx4 v[236:237], off
	v_lshl_add_u64 v[238:239], s[16:17], 0, v[130:131]
	s_mov_b32 m0, s13
	v_lshl_add_u64 v[240:241], s[16:17], 0, v[134:135]
	global_load_lds_dwordx4 v[238:239], off
	s_add_i32 m0, s13, 0x2000
	v_lshl_add_u64 v[242:243], s[8:9], 0, v[128:129]
	global_load_lds_dwordx4 v[240:241], off
	s_mov_b32 m0, s90
	v_lshl_add_u64 v[244:245], s[8:9], 0, v[132:133]
	global_load_lds_dwordx4 v[242:243], off
	s_mov_b32 m0, s91
	s_nop 0
	global_load_lds_dwordx4 v[244:245], off
	s_waitcnt vmcnt(8)
	s_waitcnt lgkmcnt(0)
	s_barrier
	s_setprio 1
	s_waitcnt lgkmcnt(0)
	v_mfma_f32_16x16x32_bf16 v[60:63], v[152:155], v[198:201], v[60:63]
	v_mfma_f32_16x16x32_bf16 v[56:59], v[172:175], v[198:201], v[56:59]
	v_mfma_f32_16x16x32_bf16 v[44:47], v[152:155], v[206:209], v[44:47]
	v_mfma_f32_16x16x32_bf16 v[40:43], v[172:175], v[206:209], v[40:43]
	v_mfma_f32_16x16x32_bf16 v[28:31], v[152:155], v[214:217], v[28:31]
	v_mfma_f32_16x16x32_bf16 v[24:27], v[172:175], v[214:217], v[24:27]
	v_mfma_f32_16x16x32_bf16 v[12:15], v[152:155], v[228:231], v[12:15]
	v_mfma_f32_16x16x32_bf16 v[8:11], v[172:175], v[228:231], v[8:11]
	v_mfma_f32_16x16x32_bf16 v[60:63], v[156:159], v[202:205], v[60:63]
	v_mfma_f32_16x16x32_bf16 v[56:59], v[176:179], v[202:205], v[56:59]
	v_mfma_f32_16x16x32_bf16 v[44:47], v[156:159], v[210:213], v[44:47]
	v_mfma_f32_16x16x32_bf16 v[40:43], v[176:179], v[210:213], v[40:43]
	v_mfma_f32_16x16x32_bf16 v[28:31], v[156:159], v[224:227], v[28:31]
	v_mfma_f32_16x16x32_bf16 v[24:27], v[176:179], v[224:227], v[24:27]
	v_mfma_f32_16x16x32_bf16 v[12:15], v[156:159], v[232:235], v[12:15]
	v_mfma_f32_16x16x32_bf16 v[8:11], v[176:179], v[232:235], v[8:11]
	s_setprio 0
	s_setprio 1
	v_mfma_f32_16x16x32_bf16 v[52:55], v[180:183], v[198:201], v[52:55]
	v_mfma_f32_16x16x32_bf16 v[48:51], v[190:193], v[198:201], v[48:51]
	v_mfma_f32_16x16x32_bf16 v[36:39], v[180:183], v[206:209], v[36:39]
	v_mfma_f32_16x16x32_bf16 v[32:35], v[190:193], v[206:209], v[32:35]
	v_mfma_f32_16x16x32_bf16 v[20:23], v[180:183], v[214:217], v[20:23]
	v_mfma_f32_16x16x32_bf16 v[16:19], v[190:193], v[214:217], v[16:19]
	v_mfma_f32_16x16x32_bf16 v[4:7], v[180:183], v[228:231], v[4:7]
	v_mfma_f32_16x16x32_bf16 v[0:3], v[190:193], v[228:231], v[0:3]
	v_mfma_f32_16x16x32_bf16 v[52:55], v[186:189], v[202:205], v[52:55]
	v_mfma_f32_16x16x32_bf16 v[48:51], v[194:197], v[202:205], v[48:51]
	v_mfma_f32_16x16x32_bf16 v[36:39], v[186:189], v[210:213], v[36:39]
	v_mfma_f32_16x16x32_bf16 v[32:35], v[194:197], v[210:213], v[32:35]
	v_mfma_f32_16x16x32_bf16 v[20:23], v[186:189], v[224:227], v[20:23]
	v_mfma_f32_16x16x32_bf16 v[16:19], v[194:197], v[224:227], v[16:19]
	v_mfma_f32_16x16x32_bf16 v[4:7], v[186:189], v[232:235], v[4:7]
	v_mfma_f32_16x16x32_bf16 v[0:3], v[194:197], v[232:235], v[0:3]
	s_setprio 0
	s_barrier
	s_add_i32 s13, 0, 0x18000
	v_add_u32_e32 v136, s13, v143
	s_add_i32 s16, 0, 0x1c000
	ds_read_b128 v[152:155], v136
	ds_read_b128 v[156:159], v136 offset:1024
	ds_read_b128 v[172:175], v136 offset:2048
	ds_read_b128 v[176:179], v136 offset:3072
	v_add_u32_e32 v136, s16, v143
	ds_read_b128 v[180:183], v136
	ds_read_b128 v[186:189], v136 offset:1024
	ds_read_b128 v[190:193], v136 offset:2048
	ds_read_b128 v[194:197], v136 offset:3072
	s_add_u32 s8, s8, s74
	s_addc_u32 s9, s9, s75
	s_mov_b32 m0, s78
	v_lshl_add_u64 v[246:247], s[8:9], 0, v[128:129]
	ds_read_b128 v[198:201], v170 offset:32768
	ds_read_b128 v[202:205], v170 offset:33792
	ds_read_b128 v[206:209], v170 offset:34816
	ds_read_b128 v[210:213], v170 offset:35840
	ds_read_b128 v[214:217], v170 offset:36864
	ds_read_b128 v[224:227], v170 offset:37888
	ds_read_b128 v[228:231], v170 offset:38912
	ds_read_b128 v[232:235], v170 offset:39936
	global_load_lds_dwordx4 v[246:247], off
	v_lshl_add_u64 v[246:247], s[8:9], 0, v[132:133]
	s_mov_b32 m0, s79
	s_nop 0
	global_load_lds_dwordx4 v[246:247], off
	s_waitcnt vmcnt(8)
	s_waitcnt lgkmcnt(0)
	s_barrier
	s_setprio 1
	s_waitcnt lgkmcnt(0)
	v_mfma_f32_16x16x32_bf16 v[124:127], v[152:155], v[198:201], v[124:127]
	v_mfma_f32_16x16x32_bf16 v[120:123], v[172:175], v[198:201], v[120:123]
	v_mfma_f32_16x16x32_bf16 v[108:111], v[152:155], v[206:209], v[108:111]
	v_mfma_f32_16x16x32_bf16 v[104:107], v[172:175], v[206:209], v[104:107]
	v_mfma_f32_16x16x32_bf16 v[92:95], v[152:155], v[214:217], v[92:95]
	v_mfma_f32_16x16x32_bf16 v[88:91], v[172:175], v[214:217], v[88:91]
	v_mfma_f32_16x16x32_bf16 v[76:79], v[152:155], v[228:231], v[76:79]
	v_mfma_f32_16x16x32_bf16 v[72:75], v[172:175], v[228:231], v[72:75]
	v_mfma_f32_16x16x32_bf16 v[124:127], v[156:159], v[202:205], v[124:127]
	v_mfma_f32_16x16x32_bf16 v[120:123], v[176:179], v[202:205], v[120:123]
	v_mfma_f32_16x16x32_bf16 v[108:111], v[156:159], v[210:213], v[108:111]
	v_mfma_f32_16x16x32_bf16 v[104:107], v[176:179], v[210:213], v[104:107]
	v_mfma_f32_16x16x32_bf16 v[92:95], v[156:159], v[224:227], v[92:95]
	v_mfma_f32_16x16x32_bf16 v[88:91], v[176:179], v[224:227], v[88:91]
	v_mfma_f32_16x16x32_bf16 v[76:79], v[156:159], v[232:235], v[76:79]
	v_mfma_f32_16x16x32_bf16 v[72:75], v[176:179], v[232:235], v[72:75]
	s_setprio 0
	s_setprio 1
	v_mfma_f32_16x16x32_bf16 v[116:119], v[180:183], v[198:201], v[116:119]
	v_mfma_f32_16x16x32_bf16 v[112:115], v[190:193], v[198:201], v[112:115]
	v_mfma_f32_16x16x32_bf16 v[100:103], v[180:183], v[206:209], v[100:103]
	v_mfma_f32_16x16x32_bf16 v[96:99], v[190:193], v[206:209], v[96:99]
	v_mfma_f32_16x16x32_bf16 v[84:87], v[180:183], v[214:217], v[84:87]
	v_mfma_f32_16x16x32_bf16 v[80:83], v[190:193], v[214:217], v[80:83]
	v_mfma_f32_16x16x32_bf16 v[68:71], v[180:183], v[228:231], v[68:71]
	v_mfma_f32_16x16x32_bf16 v[64:67], v[190:193], v[228:231], v[64:67]
	v_mfma_f32_16x16x32_bf16 v[116:119], v[186:189], v[202:205], v[116:119]
	v_mfma_f32_16x16x32_bf16 v[112:115], v[194:197], v[202:205], v[112:115]
	v_mfma_f32_16x16x32_bf16 v[100:103], v[186:189], v[210:213], v[100:103]
	v_mfma_f32_16x16x32_bf16 v[96:99], v[194:197], v[210:213], v[96:99]
	v_mfma_f32_16x16x32_bf16 v[84:87], v[186:189], v[224:227], v[84:87]
	v_mfma_f32_16x16x32_bf16 v[80:83], v[194:197], v[224:227], v[80:83]
	v_mfma_f32_16x16x32_bf16 v[68:71], v[186:189], v[232:235], v[68:71]
	v_mfma_f32_16x16x32_bf16 v[64:67], v[194:197], v[232:235], v[64:67]
	s_setprio 0
	s_barrier
	s_add_i32 s8, s13, s31
	v_lshl_add_u64 v[160:161], v[160:161], 0, s[92:93]
	s_mov_b32 m0, s8
	ds_read_b128 v[198:201], v170 offset:49152
	ds_read_b128 v[202:205], v170 offset:50176
	ds_read_b128 v[206:209], v170 offset:51200
	ds_read_b128 v[210:213], v170 offset:52224
	ds_read_b128 v[214:217], v170 offset:53248
	ds_read_b128 v[224:227], v170 offset:54272
	ds_read_b128 v[228:231], v170 offset:55296
	ds_read_b128 v[232:235], v170 offset:56320
	global_load_lds_dwordx4 v[160:161], off
	v_lshl_add_u64 v[160:161], v[236:237], 0, s[92:93]
	s_add_i32 m0, s8, 0x2000
	s_add_i32 s8, s16, s31
	global_load_lds_dwordx4 v[160:161], off
	v_lshl_add_u64 v[160:161], v[238:239], 0, s[92:93]
	s_mov_b32 m0, s8
	s_nop 0
	global_load_lds_dwordx4 v[160:161], off
	v_lshl_add_u64 v[160:161], v[240:241], 0, s[92:93]
	s_add_i32 m0, s8, 0x2000
	s_nop 0
	global_load_lds_dwordx4 v[160:161], off
	v_lshl_add_u64 v[160:161], v[242:243], 0, s[92:93]
	s_mov_b32 m0, s33
	s_nop 0
	global_load_lds_dwordx4 v[160:161], off
	v_lshl_add_u64 v[160:161], v[244:245], 0, s[92:93]
	s_mov_b32 m0, s28
	s_nop 0
	global_load_lds_dwordx4 v[160:161], off
	s_waitcnt vmcnt(8)
	s_waitcnt lgkmcnt(0)
	s_barrier
	s_setprio 1
	s_waitcnt lgkmcnt(0)
	v_mfma_f32_16x16x32_bf16 v[60:63], v[152:155], v[198:201], v[60:63]
	v_mfma_f32_16x16x32_bf16 v[56:59], v[172:175], v[198:201], v[56:59]
	v_mfma_f32_16x16x32_bf16 v[44:47], v[152:155], v[206:209], v[44:47]
	v_mfma_f32_16x16x32_bf16 v[40:43], v[172:175], v[206:209], v[40:43]
	v_mfma_f32_16x16x32_bf16 v[28:31], v[152:155], v[214:217], v[28:31]
	v_mfma_f32_16x16x32_bf16 v[24:27], v[172:175], v[214:217], v[24:27]
	v_mfma_f32_16x16x32_bf16 v[12:15], v[152:155], v[228:231], v[12:15]
	v_mfma_f32_16x16x32_bf16 v[8:11], v[172:175], v[228:231], v[8:11]
	v_mfma_f32_16x16x32_bf16 v[60:63], v[156:159], v[202:205], v[60:63]
	v_mfma_f32_16x16x32_bf16 v[56:59], v[176:179], v[202:205], v[56:59]
	v_mfma_f32_16x16x32_bf16 v[44:47], v[156:159], v[210:213], v[44:47]
	v_mfma_f32_16x16x32_bf16 v[40:43], v[176:179], v[210:213], v[40:43]
	v_mfma_f32_16x16x32_bf16 v[28:31], v[156:159], v[224:227], v[28:31]
	v_mfma_f32_16x16x32_bf16 v[24:27], v[176:179], v[224:227], v[24:27]
	v_mfma_f32_16x16x32_bf16 v[12:15], v[156:159], v[232:235], v[12:15]
	v_mfma_f32_16x16x32_bf16 v[8:11], v[176:179], v[232:235], v[8:11]
	s_setprio 0
	s_setprio 1
	v_mfma_f32_16x16x32_bf16 v[52:55], v[180:183], v[198:201], v[52:55]
	v_mfma_f32_16x16x32_bf16 v[48:51], v[190:193], v[198:201], v[48:51]
	v_mfma_f32_16x16x32_bf16 v[36:39], v[180:183], v[206:209], v[36:39]
	v_mfma_f32_16x16x32_bf16 v[32:35], v[190:193], v[206:209], v[32:35]
	v_mfma_f32_16x16x32_bf16 v[20:23], v[180:183], v[214:217], v[20:23]
	v_mfma_f32_16x16x32_bf16 v[16:19], v[190:193], v[214:217], v[16:19]
	v_mfma_f32_16x16x32_bf16 v[4:7], v[180:183], v[228:231], v[4:7]
	v_mfma_f32_16x16x32_bf16 v[0:3], v[190:193], v[228:231], v[0:3]
	v_mfma_f32_16x16x32_bf16 v[52:55], v[186:189], v[202:205], v[52:55]
	v_mfma_f32_16x16x32_bf16 v[48:51], v[194:197], v[202:205], v[48:51]
	v_mfma_f32_16x16x32_bf16 v[36:39], v[186:189], v[210:213], v[36:39]
	v_mfma_f32_16x16x32_bf16 v[32:35], v[194:197], v[210:213], v[32:35]
	v_mfma_f32_16x16x32_bf16 v[20:23], v[186:189], v[224:227], v[20:23]
	v_mfma_f32_16x16x32_bf16 v[16:19], v[194:197], v[224:227], v[16:19]
	v_mfma_f32_16x16x32_bf16 v[4:7], v[186:189], v[232:235], v[4:7]
	v_mfma_f32_16x16x32_bf16 v[0:3], v[194:197], v[232:235], v[0:3]
	s_setprio 0
	s_barrier
	s_add_u32 s6, s6, 0x100
	s_addc_u32 s7, s7, 0
	s_add_u32 s10, s10, 0x100
	s_addc_u32 s11, s11, 0
	s_cmp_ge_i32 s12, s36
	s_mov_b32 s8, s12
	s_cbranch_scc0 .LBB0_207
	s_branch .LBB0_208
.Lzx207:
	v_mov_b32_e32 v127, 0
	v_mov_b32_e32 v126, v127
	v_mov_b32_e32 v125, v127
	v_mov_b32_e32 v124, v127
	v_mov_b32_e32 v123, v127
	v_mov_b32_e32 v122, v127
	v_mov_b32_e32 v121, v127
	v_mov_b32_e32 v120, v127
	v_mov_b32_e32 v111, v127
	v_mov_b32_e32 v110, v127
	v_mov_b32_e32 v109, v127
	v_mov_b32_e32 v108, v127
	v_mov_b32_e32 v107, v127
	v_mov_b32_e32 v106, v127
	v_mov_b32_e32 v105, v127
	v_mov_b32_e32 v104, v127
	v_mov_b32_e32 v95, v127
	v_mov_b32_e32 v94, v127
	v_mov_b32_e32 v93, v127
	v_mov_b32_e32 v92, v127
	v_mov_b32_e32 v91, v127
	v_mov_b32_e32 v90, v127
	v_mov_b32_e32 v89, v127
	v_mov_b32_e32 v88, v127
	v_mov_b32_e32 v79, v127
	v_mov_b32_e32 v78, v127
	v_mov_b32_e32 v77, v127
	v_mov_b32_e32 v76, v127
	v_mov_b32_e32 v75, v127
	v_mov_b32_e32 v74, v127
	v_mov_b32_e32 v73, v127
	v_mov_b32_e32 v72, v127
	v_mov_b32_e32 v119, v127
	v_mov_b32_e32 v118, v127
	v_mov_b32_e32 v117, v127
	v_mov_b32_e32 v116, v127
	v_mov_b32_e32 v115, v127
	v_mov_b32_e32 v114, v127
	v_mov_b32_e32 v113, v127
	v_mov_b32_e32 v112, v127
	v_mov_b32_e32 v103, v127
	v_mov_b32_e32 v102, v127
	v_mov_b32_e32 v101, v127
	v_mov_b32_e32 v100, v127
	v_mov_b32_e32 v99, v127
	v_mov_b32_e32 v98, v127
	v_mov_b32_e32 v97, v127
	v_mov_b32_e32 v96, v127
	v_mov_b32_e32 v87, v127
	v_mov_b32_e32 v86, v127
	v_mov_b32_e32 v85, v127
	v_mov_b32_e32 v84, v127
	v_mov_b32_e32 v83, v127
	v_mov_b32_e32 v82, v127
	v_mov_b32_e32 v81, v127
	v_mov_b32_e32 v80, v127
	v_mov_b32_e32 v71, v127
	v_mov_b32_e32 v70, v127
	v_mov_b32_e32 v69, v127
	v_mov_b32_e32 v68, v127
	v_mov_b32_e32 v67, v127
	v_mov_b32_e32 v66, v127
	v_mov_b32_e32 v65, v127
	v_mov_b32_e32 v64, v127
	v_mov_b32_e32 v63, v127
	v_mov_b32_e32 v62, v127
	v_mov_b32_e32 v61, v127
	v_mov_b32_e32 v60, v127
	v_mov_b32_e32 v59, v127
	v_mov_b32_e32 v58, v127
	v_mov_b32_e32 v57, v127
	v_mov_b32_e32 v56, v127
	v_mov_b32_e32 v47, v127
	v_mov_b32_e32 v46, v127
	v_mov_b32_e32 v45, v127
	v_mov_b32_e32 v44, v127
	v_mov_b32_e32 v43, v127
	v_mov_b32_e32 v42, v127
	v_mov_b32_e32 v41, v127
	v_mov_b32_e32 v40, v127
	v_mov_b32_e32 v31, v127
	v_mov_b32_e32 v30, v127
	v_mov_b32_e32 v29, v127
	v_mov_b32_e32 v28, v127
	v_mov_b32_e32 v27, v127
	v_mov_b32_e32 v26, v127
	v_mov_b32_e32 v25, v127
	v_mov_b32_e32 v24, v127
	v_mov_b32_e32 v15, v127
	v_mov_b32_e32 v14, v127
	v_mov_b32_e32 v13, v127
	v_mov_b32_e32 v12, v127
	v_mov_b32_e32 v11, v127
	v_mov_b32_e32 v10, v127
	v_mov_b32_e32 v9, v127
	v_mov_b32_e32 v8, v127
	v_mov_b32_e32 v55, v127
	v_mov_b32_e32 v54, v127
	v_mov_b32_e32 v53, v127
	v_mov_b32_e32 v52, v127
	v_mov_b32_e32 v51, v127
	v_mov_b32_e32 v50, v127
	v_mov_b32_e32 v49, v127
	v_mov_b32_e32 v48, v127
	v_mov_b32_e32 v39, v127
	v_mov_b32_e32 v38, v127
	v_mov_b32_e32 v37, v127
	v_mov_b32_e32 v36, v127
	v_mov_b32_e32 v35, v127
	v_mov_b32_e32 v34, v127
	v_mov_b32_e32 v33, v127
	v_mov_b32_e32 v32, v127
	v_mov_b32_e32 v23, v127
	v_mov_b32_e32 v22, v127
	v_mov_b32_e32 v21, v127
	v_mov_b32_e32 v20, v127
	v_mov_b32_e32 v19, v127
	v_mov_b32_e32 v18, v127
	v_mov_b32_e32 v17, v127
	v_mov_b32_e32 v16, v127
	v_mov_b32_e32 v7, v127
	v_mov_b32_e32 v6, v127
	v_mov_b32_e32 v5, v127
	v_mov_b32_e32 v4, v127
	v_mov_b32_e32 v3, v127
	v_mov_b32_e32 v2, v127
	v_mov_b32_e32 v1, v127
	v_mov_b32_e32 v0, v127

.LBB0_640:
	s_and_b64 vcc, exec, s[4:5]
	s_waitcnt lgkmcnt(0)
	s_cbranch_vccnz .Lzx642
	s_add_u32 s56, s56, 0x80
	s_addc_u32 s57, s57, 0
	s_add_u32 s62, s58, 0x100
	v_mov_b32_e32 v0, 0
	s_addc_u32 s63, s59, 0
	s_mov_b32 s58, 0
	v_mov_b32_e32 v1, v0
	v_mov_b32_e32 v2, v0
	v_mov_b32_e32 v3, v0
	v_mov_b32_e32 v4, v0
	v_mov_b32_e32 v5, v0
	v_mov_b32_e32 v6, v0
	v_mov_b32_e32 v7, v0
	v_mov_b32_e32 v16, v0
	v_mov_b32_e32 v17, v0
	v_mov_b32_e32 v18, v0
	v_mov_b32_e32 v19, v0
	v_mov_b32_e32 v20, v0
	v_mov_b32_e32 v21, v0
	v_mov_b32_e32 v22, v0
	v_mov_b32_e32 v23, v0
	v_mov_b32_e32 v32, v0
	v_mov_b32_e32 v33, v0
	v_mov_b32_e32 v34, v0
	v_mov_b32_e32 v35, v0
	v_mov_b32_e32 v36, v0
	v_mov_b32_e32 v37, v0
	v_mov_b32_e32 v38, v0
	v_mov_b32_e32 v39, v0
	v_mov_b32_e32 v48, v0
	v_mov_b32_e32 v49, v0
	v_mov_b32_e32 v50, v0
	v_mov_b32_e32 v51, v0
	v_mov_b32_e32 v52, v0
	v_mov_b32_e32 v53, v0
	v_mov_b32_e32 v54, v0
	v_mov_b32_e32 v55, v0
	v_mov_b32_e32 v8, v0
	v_mov_b32_e32 v9, v0
	v_mov_b32_e32 v10, v0
	v_mov_b32_e32 v11, v0
	v_mov_b32_e32 v12, v0
	v_mov_b32_e32 v13, v0
	v_mov_b32_e32 v14, v0
	v_mov_b32_e32 v15, v0
	v_mov_b32_e32 v24, v0
	v_mov_b32_e32 v25, v0
	v_mov_b32_e32 v26, v0
	v_mov_b32_e32 v27, v0
	v_mov_b32_e32 v28, v0
	v_mov_b32_e32 v29, v0
	v_mov_b32_e32 v30, v0
	v_mov_b32_e32 v31, v0
	v_mov_b32_e32 v40, v0
	v_mov_b32_e32 v41, v0
	v_mov_b32_e32 v42, v0
	v_mov_b32_e32 v43, v0
	v_mov_b32_e32 v44, v0
	v_mov_b32_e32 v45, v0
	v_mov_b32_e32 v46, v0
	v_mov_b32_e32 v47, v0
	v_mov_b32_e32 v56, v0
	v_mov_b32_e32 v57, v0
	v_mov_b32_e32 v58, v0
	v_mov_b32_e32 v59, v0
	v_mov_b32_e32 v60, v0
	v_mov_b32_e32 v61, v0
	v_mov_b32_e32 v62, v0
	v_mov_b32_e32 v63, v0
	v_mov_b32_e32 v64, v0
	v_mov_b32_e32 v65, v0
	v_mov_b32_e32 v66, v0
	v_mov_b32_e32 v67, v0
	v_mov_b32_e32 v68, v0
	v_mov_b32_e32 v69, v0
	v_mov_b32_e32 v70, v0
	v_mov_b32_e32 v71, v0
	v_mov_b32_e32 v80, v0
	v_mov_b32_e32 v81, v0
	v_mov_b32_e32 v82, v0
	v_mov_b32_e32 v83, v0
	v_mov_b32_e32 v84, v0
	v_mov_b32_e32 v85, v0
	v_mov_b32_e32 v86, v0
	v_mov_b32_e32 v87, v0
	v_mov_b32_e32 v96, v0
	v_mov_b32_e32 v97, v0
	v_mov_b32_e32 v98, v0
	v_mov_b32_e32 v99, v0
	v_mov_b32_e32 v100, v0
	v_mov_b32_e32 v101, v0
	v_mov_b32_e32 v102, v0
	v_mov_b32_e32 v103, v0
	v_mov_b32_e32 v112, v0
	v_mov_b32_e32 v113, v0
	v_mov_b32_e32 v114, v0
	v_mov_b32_e32 v115, v0
	v_mov_b32_e32 v116, v0
	v_mov_b32_e32 v117, v0
	v_mov_b32_e32 v118, v0
	v_mov_b32_e32 v119, v0
	v_mov_b32_e32 v72, v0
	v_mov_b32_e32 v73, v0
	v_mov_b32_e32 v74, v0
	v_mov_b32_e32 v75, v0
	v_mov_b32_e32 v76, v0
	v_mov_b32_e32 v77, v0
	v_mov_b32_e32 v78, v0
	v_mov_b32_e32 v79, v0
	v_mov_b32_e32 v88, v0
	v_mov_b32_e32 v89, v0
	v_mov_b32_e32 v90, v0
	v_mov_b32_e32 v91, v0
	v_mov_b32_e32 v92, v0
	v_mov_b32_e32 v93, v0
	v_mov_b32_e32 v94, v0
	v_mov_b32_e32 v95, v0
	v_mov_b32_e32 v104, v0
	v_mov_b32_e32 v105, v0
	v_mov_b32_e32 v106, v0
	v_mov_b32_e32 v107, v0
	v_mov_b32_e32 v108, v0
	v_mov_b32_e32 v109, v0
	v_mov_b32_e32 v110, v0
	v_mov_b32_e32 v111, v0
	v_mov_b32_e32 v120, v0
	v_mov_b32_e32 v121, v0
	v_mov_b32_e32 v122, v0
	v_mov_b32_e32 v123, v0
	v_mov_b32_e32 v124, v0
	v_mov_b32_e32 v125, v0
	v_mov_b32_e32 v126, v0
	v_mov_b32_e32 v127, v0
.LBB0_642:
	ds_read_b128 v[146:149], v153
	ds_read_b128 v[156:159], v153 offset:1024
	ds_read_b128 v[160:163], v153 offset:2048
	ds_read_b128 v[164:167], v153 offset:3072
	ds_read_b128 v[168:171], v154
	ds_read_b128 v[172:175], v154 offset:1024
	ds_read_b128 v[176:179], v154 offset:2048
	ds_read_b128 v[180:183], v154 offset:3072
	s_add_i32 s64, s58, 2
	s_add_u32 s65, s56, 0x80
	s_addc_u32 s59, s57, 0
	s_cmp_eq_u32 s49, s58
	s_cselect_b32 s58, s8, s65
	s_cselect_b32 s59, s9, s59
	s_cselect_b32 s67, s43, s63
	s_cselect_b32 s66, s42, s62
	v_lshl_add_u64 v[224:225], s[56:57], 0, v[138:139]
	s_add_i32 m0, s3, 0xc000
	ds_read_b128 v[186:189], v155
	ds_read_b128 v[190:193], v155 offset:1024
	ds_read_b128 v[194:197], v155 offset:2048
	ds_read_b128 v[198:201], v155 offset:3072
	ds_read_b128 v[202:205], v155 offset:4096
	ds_read_b128 v[206:209], v155 offset:5120
	ds_read_b128 v[210:213], v155 offset:6144
	ds_read_b128 v[214:217], v155 offset:7168
	global_load_lds_dwordx4 v[224:225], off
	v_lshl_add_u64 v[224:225], s[56:57], 0, v[140:141]
	s_add_i32 m0, s3, 0xe000
	s_nop 0
	global_load_lds_dwordx4 v[224:225], off
	s_waitcnt vmcnt(8)
	s_waitcnt lgkmcnt(0)
	s_barrier
	s_setprio 1
	s_waitcnt lgkmcnt(0)
	v_mfma_f32_16x16x32_bf16 v[124:127], v[146:149], v[186:189], v[124:127]
	v_mfma_f32_16x16x32_bf16 v[120:123], v[160:163], v[186:189], v[120:123]
	v_mfma_f32_16x16x32_bf16 v[108:111], v[146:149], v[194:197], v[108:111]
	v_mfma_f32_16x16x32_bf16 v[104:107], v[160:163], v[194:197], v[104:107]
	v_mfma_f32_16x16x32_bf16 v[92:95], v[146:149], v[202:205], v[92:95]
	v_mfma_f32_16x16x32_bf16 v[88:91], v[160:163], v[202:205], v[88:91]
	v_mfma_f32_16x16x32_bf16 v[76:79], v[146:149], v[210:213], v[76:79]
	v_mfma_f32_16x16x32_bf16 v[72:75], v[160:163], v[210:213], v[72:75]
	v_mfma_f32_16x16x32_bf16 v[124:127], v[156:159], v[190:193], v[124:127]
	v_mfma_f32_16x16x32_bf16 v[120:123], v[164:167], v[190:193], v[120:123]
	v_mfma_f32_16x16x32_bf16 v[108:111], v[156:159], v[198:201], v[108:111]
	v_mfma_f32_16x16x32_bf16 v[104:107], v[164:167], v[198:201], v[104:107]
	v_mfma_f32_16x16x32_bf16 v[92:95], v[156:159], v[206:209], v[92:95]
	v_mfma_f32_16x16x32_bf16 v[88:91], v[164:167], v[206:209], v[88:91]
	v_mfma_f32_16x16x32_bf16 v[76:79], v[156:159], v[214:217], v[76:79]
	v_mfma_f32_16x16x32_bf16 v[72:75], v[164:167], v[214:217], v[72:75]
	s_setprio 0
	s_setprio 1
	v_mfma_f32_16x16x32_bf16 v[116:119], v[168:171], v[186:189], v[116:119]
	v_mfma_f32_16x16x32_bf16 v[112:115], v[176:179], v[186:189], v[112:115]
	v_mfma_f32_16x16x32_bf16 v[100:103], v[168:171], v[194:197], v[100:103]
	v_mfma_f32_16x16x32_bf16 v[96:99], v[176:179], v[194:197], v[96:99]
	v_mfma_f32_16x16x32_bf16 v[84:87], v[168:171], v[202:205], v[84:87]
	v_mfma_f32_16x16x32_bf16 v[80:83], v[176:179], v[202:205], v[80:83]
	v_mfma_f32_16x16x32_bf16 v[68:71], v[168:171], v[210:213], v[68:71]
	v_mfma_f32_16x16x32_bf16 v[64:67], v[176:179], v[210:213], v[64:67]
	v_mfma_f32_16x16x32_bf16 v[116:119], v[172:175], v[190:193], v[116:119]
	v_mfma_f32_16x16x32_bf16 v[112:115], v[180:183], v[190:193], v[112:115]
	v_mfma_f32_16x16x32_bf16 v[100:103], v[172:175], v[198:201], v[100:103]
	v_mfma_f32_16x16x32_bf16 v[96:99], v[180:183], v[198:201], v[96:99]
	v_mfma_f32_16x16x32_bf16 v[84:87], v[172:175], v[206:209], v[84:87]
	v_mfma_f32_16x16x32_bf16 v[80:83], v[180:183], v[206:209], v[80:83]
	v_mfma_f32_16x16x32_bf16 v[68:71], v[172:175], v[214:217], v[68:71]
	v_mfma_f32_16x16x32_bf16 v[64:67], v[180:183], v[214:217], v[64:67]
	s_setprio 0
	s_barrier
	s_add_i32 s65, s50, s31
	v_lshl_add_u64 v[224:225], s[66:67], 0, v[130:131]
	s_mov_b32 m0, s65
	ds_read_b128 v[186:189], v155 offset:16384
	ds_read_b128 v[190:193], v155 offset:17408
	ds_read_b128 v[194:197], v155 offset:18432
	ds_read_b128 v[198:201], v155 offset:19456
	ds_read_b128 v[202:205], v155 offset:20480
	ds_read_b128 v[206:209], v155 offset:21504
	ds_read_b128 v[210:213], v155 offset:22528
	ds_read_b128 v[214:217], v155 offset:23552
	global_load_lds_dwordx4 v[224:225], off
	s_add_i32 m0, s65, 0x2000
	v_lshl_add_u64 v[226:227], s[66:67], 0, v[134:135]
	s_add_u32 s66, s66, s18
	s_addc_u32 s67, s67, s19
	s_add_i32 s65, s51, s31
	global_load_lds_dwordx4 v[226:227], off
	v_lshl_add_u64 v[228:229], s[66:67], 0, v[130:131]
	s_mov_b32 m0, s65
	v_lshl_add_u64 v[230:231], s[66:67], 0, v[134:135]
	global_load_lds_dwordx4 v[228:229], off
	s_add_i32 m0, s65, 0x2000
	v_lshl_add_u64 v[232:233], s[58:59], 0, v[128:129]
	global_load_lds_dwordx4 v[230:231], off
	s_mov_b32 m0, s3
	v_lshl_add_u64 v[234:235], s[58:59], 0, v[132:133]
	global_load_lds_dwordx4 v[232:233], off
	s_mov_b32 m0, s28
	s_nop 0
	global_load_lds_dwordx4 v[234:235], off
	s_waitcnt vmcnt(8)
	s_waitcnt lgkmcnt(0)
	s_barrier
	s_setprio 1
	s_waitcnt lgkmcnt(0)
	v_mfma_f32_16x16x32_bf16 v[60:63], v[146:149], v[186:189], v[60:63]
	v_mfma_f32_16x16x32_bf16 v[56:59], v[160:163], v[186:189], v[56:59]
	v_mfma_f32_16x16x32_bf16 v[44:47], v[146:149], v[194:197], v[44:47]
	v_mfma_f32_16x16x32_bf16 v[40:43], v[160:163], v[194:197], v[40:43]
	v_mfma_f32_16x16x32_bf16 v[28:31], v[146:149], v[202:205], v[28:31]
	v_mfma_f32_16x16x32_bf16 v[24:27], v[160:163], v[202:205], v[24:27]
	v_mfma_f32_16x16x32_bf16 v[12:15], v[146:149], v[210:213], v[12:15]
	v_mfma_f32_16x16x32_bf16 v[8:11], v[160:163], v[210:213], v[8:11]
	v_mfma_f32_16x16x32_bf16 v[60:63], v[156:159], v[190:193], v[60:63]
	v_mfma_f32_16x16x32_bf16 v[56:59], v[164:167], v[190:193], v[56:59]
	v_mfma_f32_16x16x32_bf16 v[44:47], v[156:159], v[198:201], v[44:47]
	v_mfma_f32_16x16x32_bf16 v[40:43], v[164:167], v[198:201], v[40:43]
	v_mfma_f32_16x16x32_bf16 v[28:31], v[156:159], v[206:209], v[28:31]
	v_mfma_f32_16x16x32_bf16 v[24:27], v[164:167], v[206:209], v[24:27]
	v_mfma_f32_16x16x32_bf16 v[12:15], v[156:159], v[214:217], v[12:15]
	v_mfma_f32_16x16x32_bf16 v[8:11], v[164:167], v[214:217], v[8:11]
	s_setprio 0
	s_setprio 1
	v_mfma_f32_16x16x32_bf16 v[52:55], v[168:171], v[186:189], v[52:55]
	v_mfma_f32_16x16x32_bf16 v[48:51], v[176:179], v[186:189], v[48:51]
	v_mfma_f32_16x16x32_bf16 v[36:39], v[168:171], v[194:197], v[36:39]
	v_mfma_f32_16x16x32_bf16 v[32:35], v[176:179], v[194:197], v[32:35]
	v_mfma_f32_16x16x32_bf16 v[20:23], v[168:171], v[202:205], v[20:23]
	v_mfma_f32_16x16x32_bf16 v[16:19], v[176:179], v[202:205], v[16:19]
	v_mfma_f32_16x16x32_bf16 v[4:7], v[168:171], v[210:213], v[4:7]
	v_mfma_f32_16x16x32_bf16 v[0:3], v[176:179], v[210:213], v[0:3]
	v_mfma_f32_16x16x32_bf16 v[52:55], v[172:175], v[190:193], v[52:55]
	v_mfma_f32_16x16x32_bf16 v[48:51], v[180:183], v[190:193], v[48:51]
	v_mfma_f32_16x16x32_bf16 v[36:39], v[172:175], v[198:201], v[36:39]
	v_mfma_f32_16x16x32_bf16 v[32:35], v[180:183], v[198:201], v[32:35]
	v_mfma_f32_16x16x32_bf16 v[20:23], v[172:175], v[206:209], v[20:23]
	v_mfma_f32_16x16x32_bf16 v[16:19], v[180:183], v[206:209], v[16:19]
	v_mfma_f32_16x16x32_bf16 v[4:7], v[172:175], v[214:217], v[4:7]
	v_mfma_f32_16x16x32_bf16 v[0:3], v[180:183], v[214:217], v[0:3]
	s_setprio 0
	s_barrier
	s_add_i32 s65, 0, 0x18000
	v_add_u32_e32 v136, s65, v151
	s_add_i32 s66, 0, 0x1c000
	ds_read_b128 v[146:149], v136
	ds_read_b128 v[156:159], v136 offset:1024
	ds_read_b128 v[160:163], v136 offset:2048
	ds_read_b128 v[164:167], v136 offset:3072
	v_add_u32_e32 v136, s66, v151
	ds_read_b128 v[168:171], v136
	ds_read_b128 v[172:175], v136 offset:1024
	ds_read_b128 v[176:179], v136 offset:2048
	ds_read_b128 v[180:183], v136 offset:3072
	s_add_u32 s58, s58, s18
	s_addc_u32 s59, s59, s19
	s_mov_b32 m0, s33
	v_lshl_add_u64 v[236:237], s[58:59], 0, v[128:129]
	ds_read_b128 v[186:189], v155 offset:32768
	ds_read_b128 v[190:193], v155 offset:33792
	ds_read_b128 v[194:197], v155 offset:34816
	ds_read_b128 v[198:201], v155 offset:35840
	ds_read_b128 v[202:205], v155 offset:36864
	ds_read_b128 v[206:209], v155 offset:37888
	ds_read_b128 v[210:213], v155 offset:38912
	ds_read_b128 v[214:217], v155 offset:39936
	global_load_lds_dwordx4 v[236:237], off
	v_lshl_add_u64 v[236:237], s[58:59], 0, v[132:133]
	s_mov_b32 m0, s44
	s_nop 0
	global_load_lds_dwordx4 v[236:237], off
	s_waitcnt vmcnt(8)
	s_waitcnt lgkmcnt(0)
	s_barrier
	s_setprio 1
	s_waitcnt lgkmcnt(0)
	v_mfma_f32_16x16x32_bf16 v[124:127], v[146:149], v[186:189], v[124:127]
	v_mfma_f32_16x16x32_bf16 v[120:123], v[160:163], v[186:189], v[120:123]
	v_mfma_f32_16x16x32_bf16 v[108:111], v[146:149], v[194:197], v[108:111]
	v_mfma_f32_16x16x32_bf16 v[104:107], v[160:163], v[194:197], v[104:107]
	v_mfma_f32_16x16x32_bf16 v[92:95], v[146:149], v[202:205], v[92:95]
	v_mfma_f32_16x16x32_bf16 v[88:91], v[160:163], v[202:205], v[88:91]
	v_mfma_f32_16x16x32_bf16 v[76:79], v[146:149], v[210:213], v[76:79]
	v_mfma_f32_16x16x32_bf16 v[72:75], v[160:163], v[210:213], v[72:75]
	v_mfma_f32_16x16x32_bf16 v[124:127], v[156:159], v[190:193], v[124:127]
	v_mfma_f32_16x16x32_bf16 v[120:123], v[164:167], v[190:193], v[120:123]
	v_mfma_f32_16x16x32_bf16 v[108:111], v[156:159], v[198:201], v[108:111]
	v_mfma_f32_16x16x32_bf16 v[104:107], v[164:167], v[198:201], v[104:107]
	v_mfma_f32_16x16x32_bf16 v[92:95], v[156:159], v[206:209], v[92:95]
	v_mfma_f32_16x16x32_bf16 v[88:91], v[164:167], v[206:209], v[88:91]
	v_mfma_f32_16x16x32_bf16 v[76:79], v[156:159], v[214:217], v[76:79]
	v_mfma_f32_16x16x32_bf16 v[72:75], v[164:167], v[214:217], v[72:75]
	s_setprio 0
	s_setprio 1
	v_mfma_f32_16x16x32_bf16 v[116:119], v[168:171], v[186:189], v[116:119]
	v_mfma_f32_16x16x32_bf16 v[112:115], v[176:179], v[186:189], v[112:115]
	v_mfma_f32_16x16x32_bf16 v[100:103], v[168:171], v[194:197], v[100:103]
	v_mfma_f32_16x16x32_bf16 v[96:99], v[176:179], v[194:197], v[96:99]
	v_mfma_f32_16x16x32_bf16 v[84:87], v[168:171], v[202:205], v[84:87]
	v_mfma_f32_16x16x32_bf16 v[80:83], v[176:179], v[202:205], v[80:83]
	v_mfma_f32_16x16x32_bf16 v[68:71], v[168:171], v[210:213], v[68:71]
	v_mfma_f32_16x16x32_bf16 v[64:67], v[176:179], v[210:213], v[64:67]
	v_mfma_f32_16x16x32_bf16 v[116:119], v[172:175], v[190:193], v[116:119]
	v_mfma_f32_16x16x32_bf16 v[112:115], v[180:183], v[190:193], v[112:115]
	v_mfma_f32_16x16x32_bf16 v[100:103], v[172:175], v[198:201], v[100:103]
	v_mfma_f32_16x16x32_bf16 v[96:99], v[180:183], v[198:201], v[96:99]
	v_mfma_f32_16x16x32_bf16 v[84:87], v[172:175], v[206:209], v[84:87]
	v_mfma_f32_16x16x32_bf16 v[80:83], v[180:183], v[206:209], v[80:83]
	v_mfma_f32_16x16x32_bf16 v[68:71], v[172:175], v[214:217], v[68:71]
	v_mfma_f32_16x16x32_bf16 v[64:67], v[180:183], v[214:217], v[64:67]
	s_setprio 0
	s_barrier
	s_add_i32 s58, s65, s31
	v_lshl_add_u64 v[224:225], v[224:225], 0, s[40:41]
	s_mov_b32 m0, s58
	ds_read_b128 v[186:189], v155 offset:49152
	ds_read_b128 v[190:193], v155 offset:50176
	ds_read_b128 v[194:197], v155 offset:51200
	ds_read_b128 v[198:201], v155 offset:52224
	ds_read_b128 v[202:205], v155 offset:53248
	ds_read_b128 v[206:209], v155 offset:54272
	ds_read_b128 v[210:213], v155 offset:55296
	ds_read_b128 v[214:217], v155 offset:56320
	global_load_lds_dwordx4 v[224:225], off
	v_lshl_add_u64 v[224:225], v[226:227], 0, s[40:41]
	s_add_i32 m0, s58, 0x2000
	s_add_i32 s58, s66, s31
	global_load_lds_dwordx4 v[224:225], off
	v_lshl_add_u64 v[224:225], v[228:229], 0, s[40:41]
	s_mov_b32 m0, s58
	s_nop 0
	global_load_lds_dwordx4 v[224:225], off
	v_lshl_add_u64 v[224:225], v[230:231], 0, s[40:41]
	s_add_i32 m0, s58, 0x2000
	s_nop 0
	global_load_lds_dwordx4 v[224:225], off
	v_lshl_add_u64 v[224:225], v[232:233], 0, s[40:41]
	s_mov_b32 m0, s47
	s_nop 0
	global_load_lds_dwordx4 v[224:225], off
	v_lshl_add_u64 v[224:225], v[234:235], 0, s[40:41]
	s_mov_b32 m0, s48
	s_nop 0
	global_load_lds_dwordx4 v[224:225], off
	s_waitcnt vmcnt(8)
	s_waitcnt lgkmcnt(0)
	s_barrier
	s_setprio 1
	s_waitcnt lgkmcnt(0)
	v_mfma_f32_16x16x32_bf16 v[60:63], v[146:149], v[186:189], v[60:63]
	v_mfma_f32_16x16x32_bf16 v[56:59], v[160:163], v[186:189], v[56:59]
	v_mfma_f32_16x16x32_bf16 v[44:47], v[146:149], v[194:197], v[44:47]
	v_mfma_f32_16x16x32_bf16 v[40:43], v[160:163], v[194:197], v[40:43]
	v_mfma_f32_16x16x32_bf16 v[28:31], v[146:149], v[202:205], v[28:31]
	v_mfma_f32_16x16x32_bf16 v[24:27], v[160:163], v[202:205], v[24:27]
	v_mfma_f32_16x16x32_bf16 v[12:15], v[146:149], v[210:213], v[12:15]
	v_mfma_f32_16x16x32_bf16 v[8:11], v[160:163], v[210:213], v[8:11]
	v_mfma_f32_16x16x32_bf16 v[60:63], v[156:159], v[190:193], v[60:63]
	v_mfma_f32_16x16x32_bf16 v[56:59], v[164:167], v[190:193], v[56:59]
	v_mfma_f32_16x16x32_bf16 v[44:47], v[156:159], v[198:201], v[44:47]
	v_mfma_f32_16x16x32_bf16 v[40:43], v[164:167], v[198:201], v[40:43]
	v_mfma_f32_16x16x32_bf16 v[28:31], v[156:159], v[206:209], v[28:31]
	v_mfma_f32_16x16x32_bf16 v[24:27], v[164:167], v[206:209], v[24:27]
	v_mfma_f32_16x16x32_bf16 v[12:15], v[156:159], v[214:217], v[12:15]
	v_mfma_f32_16x16x32_bf16 v[8:11], v[164:167], v[214:217], v[8:11]
	s_setprio 0
	s_setprio 1
	v_mfma_f32_16x16x32_bf16 v[52:55], v[168:171], v[186:189], v[52:55]
	v_mfma_f32_16x16x32_bf16 v[48:51], v[176:179], v[186:189], v[48:51]
	v_mfma_f32_16x16x32_bf16 v[36:39], v[168:171], v[194:197], v[36:39]
	v_mfma_f32_16x16x32_bf16 v[32:35], v[176:179], v[194:197], v[32:35]
	v_mfma_f32_16x16x32_bf16 v[20:23], v[168:171], v[202:205], v[20:23]
	v_mfma_f32_16x16x32_bf16 v[16:19], v[176:179], v[202:205], v[16:19]
	v_mfma_f32_16x16x32_bf16 v[4:7], v[168:171], v[210:213], v[4:7]
	v_mfma_f32_16x16x32_bf16 v[0:3], v[176:179], v[210:213], v[0:3]
	v_mfma_f32_16x16x32_bf16 v[52:55], v[172:175], v[190:193], v[52:55]
	v_mfma_f32_16x16x32_bf16 v[48:51], v[180:183], v[190:193], v[48:51]
	v_mfma_f32_16x16x32_bf16 v[36:39], v[172:175], v[198:201], v[36:39]
	v_mfma_f32_16x16x32_bf16 v[32:35], v[180:183], v[198:201], v[32:35]
	v_mfma_f32_16x16x32_bf16 v[20:23], v[172:175], v[206:209], v[20:23]
	v_mfma_f32_16x16x32_bf16 v[16:19], v[180:183], v[206:209], v[16:19]
	v_mfma_f32_16x16x32_bf16 v[4:7], v[172:175], v[214:217], v[4:7]
	v_mfma_f32_16x16x32_bf16 v[0:3], v[180:183], v[214:217], v[0:3]
	s_setprio 0
	s_barrier
	s_add_u32 s56, s56, 0x100
	s_addc_u32 s57, s57, 0
	s_add_u32 s62, s62, 0x100
	s_addc_u32 s63, s63, 0
	s_cmp_ge_i32 s64, s45
	s_mov_b32 s58, s64
	s_cbranch_scc0 .LBB0_642
	s_branch .LBB0_643

.LBB0_677:
	s_andn2_b64 vcc, exec, s[42:43]
	s_cbranch_vccnz .Lzx679
	s_add_u32 s58, s58, 0x80
	s_addc_u32 s59, s59, 0
	s_add_u32 s71, s60, 0x100
	v_mov_b32_e32 v0, 0
	s_addc_u32 s78, s61, 0
	s_mov_b32 s60, 0
	v_mov_b32_e32 v1, v0
	v_mov_b32_e32 v2, v0
	v_mov_b32_e32 v3, v0
	v_mov_b32_e32 v4, v0
	v_mov_b32_e32 v5, v0
	v_mov_b32_e32 v6, v0
	v_mov_b32_e32 v7, v0
	v_mov_b32_e32 v16, v0
	v_mov_b32_e32 v17, v0
	v_mov_b32_e32 v18, v0
	v_mov_b32_e32 v19, v0
	v_mov_b32_e32 v20, v0
	v_mov_b32_e32 v21, v0
	v_mov_b32_e32 v22, v0
	v_mov_b32_e32 v23, v0
	v_mov_b32_e32 v32, v0
	v_mov_b32_e32 v33, v0
	v_mov_b32_e32 v34, v0
	v_mov_b32_e32 v35, v0
	v_mov_b32_e32 v36, v0
	v_mov_b32_e32 v37, v0
	v_mov_b32_e32 v38, v0
	v_mov_b32_e32 v39, v0
	v_mov_b32_e32 v48, v0
	v_mov_b32_e32 v49, v0
	v_mov_b32_e32 v50, v0
	v_mov_b32_e32 v51, v0
	v_mov_b32_e32 v52, v0
	v_mov_b32_e32 v53, v0
	v_mov_b32_e32 v54, v0
	v_mov_b32_e32 v55, v0
	v_mov_b32_e32 v8, v0
	v_mov_b32_e32 v9, v0
	v_mov_b32_e32 v10, v0
	v_mov_b32_e32 v11, v0
	v_mov_b32_e32 v12, v0
	v_mov_b32_e32 v13, v0
	v_mov_b32_e32 v14, v0
	v_mov_b32_e32 v15, v0
	v_mov_b32_e32 v24, v0
	v_mov_b32_e32 v25, v0
	v_mov_b32_e32 v26, v0
	v_mov_b32_e32 v27, v0
	v_mov_b32_e32 v28, v0
	v_mov_b32_e32 v29, v0
	v_mov_b32_e32 v30, v0
	v_mov_b32_e32 v31, v0
	v_mov_b32_e32 v40, v0
	v_mov_b32_e32 v41, v0
	v_mov_b32_e32 v42, v0
	v_mov_b32_e32 v43, v0
	v_mov_b32_e32 v44, v0
	v_mov_b32_e32 v45, v0
	v_mov_b32_e32 v46, v0
	v_mov_b32_e32 v47, v0
	v_mov_b32_e32 v56, v0
	v_mov_b32_e32 v57, v0
	v_mov_b32_e32 v58, v0
	v_mov_b32_e32 v59, v0
	v_mov_b32_e32 v60, v0
	v_mov_b32_e32 v61, v0
	v_mov_b32_e32 v62, v0
	v_mov_b32_e32 v63, v0
	v_mov_b32_e32 v64, v0
	v_mov_b32_e32 v65, v0
	v_mov_b32_e32 v66, v0
	v_mov_b32_e32 v67, v0
	v_mov_b32_e32 v68, v0
	v_mov_b32_e32 v69, v0
	v_mov_b32_e32 v70, v0
	v_mov_b32_e32 v71, v0
	v_mov_b32_e32 v80, v0
	v_mov_b32_e32 v81, v0
	v_mov_b32_e32 v82, v0
	v_mov_b32_e32 v83, v0
	v_mov_b32_e32 v84, v0
	v_mov_b32_e32 v85, v0
	v_mov_b32_e32 v86, v0
	v_mov_b32_e32 v87, v0
	v_mov_b32_e32 v96, v0
	v_mov_b32_e32 v97, v0
	v_mov_b32_e32 v98, v0
	v_mov_b32_e32 v99, v0
	v_mov_b32_e32 v100, v0
	v_mov_b32_e32 v101, v0
	v_mov_b32_e32 v102, v0
	v_mov_b32_e32 v103, v0
	v_mov_b32_e32 v112, v0
	v_mov_b32_e32 v113, v0
	v_mov_b32_e32 v114, v0
	v_mov_b32_e32 v115, v0
	v_mov_b32_e32 v116, v0
	v_mov_b32_e32 v117, v0
	v_mov_b32_e32 v118, v0
	v_mov_b32_e32 v119, v0
	v_mov_b32_e32 v72, v0
	v_mov_b32_e32 v73, v0
	v_mov_b32_e32 v74, v0
	v_mov_b32_e32 v75, v0
	v_mov_b32_e32 v76, v0
	v_mov_b32_e32 v77, v0
	v_mov_b32_e32 v78, v0
	v_mov_b32_e32 v79, v0
	v_mov_b32_e32 v88, v0
	v_mov_b32_e32 v89, v0
	v_mov_b32_e32 v90, v0
	v_mov_b32_e32 v91, v0
	v_mov_b32_e32 v92, v0
	v_mov_b32_e32 v93, v0
	v_mov_b32_e32 v94, v0
	v_mov_b32_e32 v95, v0
	v_mov_b32_e32 v104, v0
	v_mov_b32_e32 v105, v0
	v_mov_b32_e32 v106, v0
	v_mov_b32_e32 v107, v0
	v_mov_b32_e32 v108, v0
	v_mov_b32_e32 v109, v0
	v_mov_b32_e32 v110, v0
	v_mov_b32_e32 v111, v0
	v_mov_b32_e32 v124, v0
	v_mov_b32_e32 v125, v0
	v_mov_b32_e32 v126, v0
	v_mov_b32_e32 v127, v0
	v_mov_b32_e32 v120, v0
	v_mov_b32_e32 v121, v0
	v_mov_b32_e32 v122, v0
	v_mov_b32_e32 v123, v0
.LBB0_679:
	ds_read_b128 v[150:153], v147
	ds_read_b128 v[154:157], v147 offset:1024
	ds_read_b128 v[158:161], v147 offset:2048
	ds_read_b128 v[162:165], v147 offset:3072
	ds_read_b128 v[166:169], v148
	ds_read_b128 v[170:173], v148 offset:1024
	ds_read_b128 v[174:177], v148 offset:2048
	ds_read_b128 v[178:181], v148 offset:3072
	s_add_i32 s79, s60, 2
	s_add_u32 s80, s58, 0x80
	s_addc_u32 s61, s59, 0
	s_cmp_eq_u32 s65, s60
	s_cselect_b32 s60, s4, s80
	s_cselect_b32 s61, s5, s61
	s_cselect_b32 s81, s57, s78
	s_cselect_b32 s80, s56, s71
	v_lshl_add_u64 v[182:183], s[58:59], 0, v[136:137]
	s_add_i32 m0, s45, 0xc000
	ds_read_b128 v[186:189], v149
	ds_read_b128 v[190:193], v149 offset:1024
	ds_read_b128 v[194:197], v149 offset:2048
	ds_read_b128 v[198:201], v149 offset:3072
	ds_read_b128 v[202:205], v149 offset:4096
	ds_read_b128 v[206:209], v149 offset:5120
	ds_read_b128 v[210:213], v149 offset:6144
	ds_read_b128 v[214:217], v149 offset:7168
	global_load_lds_dwordx4 v[182:183], off
	v_lshl_add_u64 v[182:183], s[58:59], 0, v[138:139]
	s_add_i32 m0, s45, 0xe000
	s_nop 0
	global_load_lds_dwordx4 v[182:183], off
	s_waitcnt vmcnt(8)
	s_waitcnt lgkmcnt(0)
	s_barrier
	s_setprio 1
	s_waitcnt lgkmcnt(0)
	v_mfma_f32_16x16x32_bf16 v[120:123], v[150:153], v[186:189], v[120:123]
	v_mfma_f32_16x16x32_bf16 v[124:127], v[158:161], v[186:189], v[124:127]
	v_mfma_f32_16x16x32_bf16 v[108:111], v[150:153], v[194:197], v[108:111]
	v_mfma_f32_16x16x32_bf16 v[104:107], v[158:161], v[194:197], v[104:107]
	v_mfma_f32_16x16x32_bf16 v[92:95], v[150:153], v[202:205], v[92:95]
	v_mfma_f32_16x16x32_bf16 v[88:91], v[158:161], v[202:205], v[88:91]
	v_mfma_f32_16x16x32_bf16 v[76:79], v[150:153], v[210:213], v[76:79]
	v_mfma_f32_16x16x32_bf16 v[72:75], v[158:161], v[210:213], v[72:75]
	v_mfma_f32_16x16x32_bf16 v[120:123], v[154:157], v[190:193], v[120:123]
	v_mfma_f32_16x16x32_bf16 v[124:127], v[162:165], v[190:193], v[124:127]
	v_mfma_f32_16x16x32_bf16 v[108:111], v[154:157], v[198:201], v[108:111]
	v_mfma_f32_16x16x32_bf16 v[104:107], v[162:165], v[198:201], v[104:107]
	v_mfma_f32_16x16x32_bf16 v[92:95], v[154:157], v[206:209], v[92:95]
	v_mfma_f32_16x16x32_bf16 v[88:91], v[162:165], v[206:209], v[88:91]
	v_mfma_f32_16x16x32_bf16 v[76:79], v[154:157], v[214:217], v[76:79]
	v_mfma_f32_16x16x32_bf16 v[72:75], v[162:165], v[214:217], v[72:75]
	s_setprio 0
	s_setprio 1
	v_mfma_f32_16x16x32_bf16 v[116:119], v[166:169], v[186:189], v[116:119]
	v_mfma_f32_16x16x32_bf16 v[112:115], v[174:177], v[186:189], v[112:115]
	v_mfma_f32_16x16x32_bf16 v[100:103], v[166:169], v[194:197], v[100:103]
	v_mfma_f32_16x16x32_bf16 v[96:99], v[174:177], v[194:197], v[96:99]
	v_mfma_f32_16x16x32_bf16 v[84:87], v[166:169], v[202:205], v[84:87]
	v_mfma_f32_16x16x32_bf16 v[80:83], v[174:177], v[202:205], v[80:83]
	v_mfma_f32_16x16x32_bf16 v[68:71], v[166:169], v[210:213], v[68:71]
	v_mfma_f32_16x16x32_bf16 v[64:67], v[174:177], v[210:213], v[64:67]
	v_mfma_f32_16x16x32_bf16 v[116:119], v[170:173], v[190:193], v[116:119]
	v_mfma_f32_16x16x32_bf16 v[112:115], v[178:181], v[190:193], v[112:115]
	v_mfma_f32_16x16x32_bf16 v[100:103], v[170:173], v[198:201], v[100:103]
	v_mfma_f32_16x16x32_bf16 v[96:99], v[178:181], v[198:201], v[96:99]
	v_mfma_f32_16x16x32_bf16 v[84:87], v[170:173], v[206:209], v[84:87]
	v_mfma_f32_16x16x32_bf16 v[80:83], v[178:181], v[206:209], v[80:83]
	v_mfma_f32_16x16x32_bf16 v[68:71], v[170:173], v[214:217], v[68:71]
	v_mfma_f32_16x16x32_bf16 v[64:67], v[178:181], v[214:217], v[64:67]
	s_setprio 0
	s_barrier
	s_add_i32 s82, s66, s31
	v_lshl_add_u64 v[182:183], s[80:81], 0, v[132:133]
	s_mov_b32 m0, s82
	ds_read_b128 v[186:189], v149 offset:16384
	ds_read_b128 v[190:193], v149 offset:17408
	ds_read_b128 v[194:197], v149 offset:18432
	ds_read_b128 v[198:201], v149 offset:19456
	ds_read_b128 v[202:205], v149 offset:20480
	ds_read_b128 v[206:209], v149 offset:21504
	ds_read_b128 v[210:213], v149 offset:22528
	ds_read_b128 v[214:217], v149 offset:23552
	global_load_lds_dwordx4 v[182:183], off
	s_add_i32 m0, s82, 0x2000
	v_lshl_add_u64 v[224:225], s[80:81], 0, v[128:129]
	s_add_u32 s80, s80, s36
	s_addc_u32 s81, s81, s37
	s_add_i32 s82, s67, s31
	global_load_lds_dwordx4 v[224:225], off
	v_lshl_add_u64 v[226:227], s[80:81], 0, v[132:133]
	s_mov_b32 m0, s82
	v_lshl_add_u64 v[228:229], s[80:81], 0, v[128:129]
	global_load_lds_dwordx4 v[226:227], off
	s_add_i32 m0, s82, 0x2000
	v_lshl_add_u64 v[230:231], s[60:61], 0, v[134:135]
	global_load_lds_dwordx4 v[228:229], off
	s_mov_b32 m0, s45
	v_lshl_add_u64 v[232:233], s[60:61], 0, v[130:131]
	global_load_lds_dwordx4 v[230:231], off
	s_mov_b32 m0, s46
	s_nop 0
	global_load_lds_dwordx4 v[232:233], off
	s_waitcnt vmcnt(8)
	s_waitcnt lgkmcnt(0)
	s_barrier
	s_setprio 1
	s_waitcnt lgkmcnt(0)
	v_mfma_f32_16x16x32_bf16 v[60:63], v[150:153], v[186:189], v[60:63]
	v_mfma_f32_16x16x32_bf16 v[56:59], v[158:161], v[186:189], v[56:59]
	v_mfma_f32_16x16x32_bf16 v[44:47], v[150:153], v[194:197], v[44:47]
	v_mfma_f32_16x16x32_bf16 v[40:43], v[158:161], v[194:197], v[40:43]
	v_mfma_f32_16x16x32_bf16 v[28:31], v[150:153], v[202:205], v[28:31]
	v_mfma_f32_16x16x32_bf16 v[24:27], v[158:161], v[202:205], v[24:27]
	v_mfma_f32_16x16x32_bf16 v[12:15], v[150:153], v[210:213], v[12:15]
	v_mfma_f32_16x16x32_bf16 v[8:11], v[158:161], v[210:213], v[8:11]
	v_mfma_f32_16x16x32_bf16 v[60:63], v[154:157], v[190:193], v[60:63]
	v_mfma_f32_16x16x32_bf16 v[56:59], v[162:165], v[190:193], v[56:59]
	v_mfma_f32_16x16x32_bf16 v[44:47], v[154:157], v[198:201], v[44:47]
	v_mfma_f32_16x16x32_bf16 v[40:43], v[162:165], v[198:201], v[40:43]
	v_mfma_f32_16x16x32_bf16 v[28:31], v[154:157], v[206:209], v[28:31]
	v_mfma_f32_16x16x32_bf16 v[24:27], v[162:165], v[206:209], v[24:27]
	v_mfma_f32_16x16x32_bf16 v[12:15], v[154:157], v[214:217], v[12:15]
	v_mfma_f32_16x16x32_bf16 v[8:11], v[162:165], v[214:217], v[8:11]
	s_setprio 0
	s_setprio 1
	v_mfma_f32_16x16x32_bf16 v[52:55], v[166:169], v[186:189], v[52:55]
	v_mfma_f32_16x16x32_bf16 v[48:51], v[174:177], v[186:189], v[48:51]
	v_mfma_f32_16x16x32_bf16 v[36:39], v[166:169], v[194:197], v[36:39]
	v_mfma_f32_16x16x32_bf16 v[32:35], v[174:177], v[194:197], v[32:35]
	v_mfma_f32_16x16x32_bf16 v[20:23], v[166:169], v[202:205], v[20:23]
	v_mfma_f32_16x16x32_bf16 v[16:19], v[174:177], v[202:205], v[16:19]
	v_mfma_f32_16x16x32_bf16 v[4:7], v[166:169], v[210:213], v[4:7]
	v_mfma_f32_16x16x32_bf16 v[0:3], v[174:177], v[210:213], v[0:3]
	v_mfma_f32_16x16x32_bf16 v[52:55], v[170:173], v[190:193], v[52:55]
	v_mfma_f32_16x16x32_bf16 v[48:51], v[178:181], v[190:193], v[48:51]
	v_mfma_f32_16x16x32_bf16 v[36:39], v[170:173], v[198:201], v[36:39]
	v_mfma_f32_16x16x32_bf16 v[32:35], v[178:181], v[198:201], v[32:35]
	v_mfma_f32_16x16x32_bf16 v[20:23], v[170:173], v[206:209], v[20:23]
	v_mfma_f32_16x16x32_bf16 v[16:19], v[178:181], v[206:209], v[16:19]
	v_mfma_f32_16x16x32_bf16 v[4:7], v[170:173], v[214:217], v[4:7]
	v_mfma_f32_16x16x32_bf16 v[0:3], v[178:181], v[214:217], v[0:3]
	s_setprio 0
	s_barrier
	s_add_i32 s80, 0, 0x18000
	s_add_i32 s81, 0, 0x1c000
	v_add_u32_e32 v162, s80, v145
	v_add_u32_e32 v178, s81, v145
	ds_read_b128 v[150:153], v162
	ds_read_b128 v[154:157], v162 offset:1024
	ds_read_b128 v[158:161], v162 offset:2048
	ds_read_b128 v[162:165], v162 offset:3072
	ds_read_b128 v[166:169], v178
	ds_read_b128 v[170:173], v178 offset:1024
	ds_read_b128 v[174:177], v178 offset:2048
	ds_read_b128 v[178:181], v178 offset:3072
	s_add_u32 s60, s60, s36
	s_addc_u32 s61, s61, s37
	s_mov_b32 m0, s47
	v_lshl_add_u64 v[234:235], s[60:61], 0, v[134:135]
	ds_read_b128 v[186:189], v149 offset:32768
	ds_read_b128 v[190:193], v149 offset:33792
	ds_read_b128 v[194:197], v149 offset:34816
	ds_read_b128 v[198:201], v149 offset:35840
	ds_read_b128 v[202:205], v149 offset:36864
	ds_read_b128 v[206:209], v149 offset:37888
	ds_read_b128 v[210:213], v149 offset:38912
	ds_read_b128 v[214:217], v149 offset:39936
	global_load_lds_dwordx4 v[234:235], off
	v_lshl_add_u64 v[234:235], s[60:61], 0, v[130:131]
	s_mov_b32 m0, s48
	s_nop 0
	global_load_lds_dwordx4 v[234:235], off
	s_waitcnt vmcnt(8)
	s_waitcnt lgkmcnt(0)
	s_barrier
	s_setprio 1
	s_waitcnt lgkmcnt(0)
	v_mfma_f32_16x16x32_bf16 v[120:123], v[150:153], v[186:189], v[120:123]
	v_mfma_f32_16x16x32_bf16 v[124:127], v[158:161], v[186:189], v[124:127]
	v_mfma_f32_16x16x32_bf16 v[108:111], v[150:153], v[194:197], v[108:111]
	v_mfma_f32_16x16x32_bf16 v[104:107], v[158:161], v[194:197], v[104:107]
	v_mfma_f32_16x16x32_bf16 v[92:95], v[150:153], v[202:205], v[92:95]
	v_mfma_f32_16x16x32_bf16 v[88:91], v[158:161], v[202:205], v[88:91]
	v_mfma_f32_16x16x32_bf16 v[76:79], v[150:153], v[210:213], v[76:79]
	v_mfma_f32_16x16x32_bf16 v[72:75], v[158:161], v[210:213], v[72:75]
	v_mfma_f32_16x16x32_bf16 v[120:123], v[154:157], v[190:193], v[120:123]
	v_mfma_f32_16x16x32_bf16 v[124:127], v[162:165], v[190:193], v[124:127]
	v_mfma_f32_16x16x32_bf16 v[108:111], v[154:157], v[198:201], v[108:111]
	v_mfma_f32_16x16x32_bf16 v[104:107], v[162:165], v[198:201], v[104:107]
	v_mfma_f32_16x16x32_bf16 v[92:95], v[154:157], v[206:209], v[92:95]
	v_mfma_f32_16x16x32_bf16 v[88:91], v[162:165], v[206:209], v[88:91]
	v_mfma_f32_16x16x32_bf16 v[76:79], v[154:157], v[214:217], v[76:79]
	v_mfma_f32_16x16x32_bf16 v[72:75], v[162:165], v[214:217], v[72:75]
	s_setprio 0
	s_setprio 1
	v_mfma_f32_16x16x32_bf16 v[116:119], v[166:169], v[186:189], v[116:119]
	v_mfma_f32_16x16x32_bf16 v[112:115], v[174:177], v[186:189], v[112:115]
	v_mfma_f32_16x16x32_bf16 v[100:103], v[166:169], v[194:197], v[100:103]
	v_mfma_f32_16x16x32_bf16 v[96:99], v[174:177], v[194:197], v[96:99]
	v_mfma_f32_16x16x32_bf16 v[84:87], v[166:169], v[202:205], v[84:87]
	v_mfma_f32_16x16x32_bf16 v[80:83], v[174:177], v[202:205], v[80:83]
	v_mfma_f32_16x16x32_bf16 v[68:71], v[166:169], v[210:213], v[68:71]
	v_mfma_f32_16x16x32_bf16 v[64:67], v[174:177], v[210:213], v[64:67]
	v_mfma_f32_16x16x32_bf16 v[116:119], v[170:173], v[190:193], v[116:119]
	v_mfma_f32_16x16x32_bf16 v[112:115], v[178:181], v[190:193], v[112:115]
	v_mfma_f32_16x16x32_bf16 v[100:103], v[170:173], v[198:201], v[100:103]
	v_mfma_f32_16x16x32_bf16 v[96:99], v[178:181], v[198:201], v[96:99]
	v_mfma_f32_16x16x32_bf16 v[84:87], v[170:173], v[206:209], v[84:87]
	v_mfma_f32_16x16x32_bf16 v[80:83], v[178:181], v[206:209], v[80:83]
	v_mfma_f32_16x16x32_bf16 v[68:71], v[170:173], v[214:217], v[68:71]
	v_mfma_f32_16x16x32_bf16 v[64:67], v[178:181], v[214:217], v[64:67]
	s_setprio 0
	s_barrier
	s_add_i32 s60, s80, s31
	v_lshl_add_u64 v[182:183], v[182:183], 0, s[40:41]
	s_mov_b32 m0, s60
	ds_read_b128 v[186:189], v149 offset:49152
	ds_read_b128 v[190:193], v149 offset:50176
	ds_read_b128 v[194:197], v149 offset:51200
	ds_read_b128 v[198:201], v149 offset:52224
	ds_read_b128 v[202:205], v149 offset:53248
	ds_read_b128 v[206:209], v149 offset:54272
	ds_read_b128 v[210:213], v149 offset:55296
	ds_read_b128 v[214:217], v149 offset:56320
	global_load_lds_dwordx4 v[182:183], off
	v_lshl_add_u64 v[182:183], v[224:225], 0, s[40:41]
	s_add_i32 m0, s60, 0x2000
	s_add_i32 s60, s81, s31
	global_load_lds_dwordx4 v[182:183], off
	v_lshl_add_u64 v[182:183], v[226:227], 0, s[40:41]
	s_mov_b32 m0, s60
	s_nop 0
	global_load_lds_dwordx4 v[182:183], off
	v_lshl_add_u64 v[182:183], v[228:229], 0, s[40:41]
	s_add_i32 m0, s60, 0x2000
	s_nop 0
	global_load_lds_dwordx4 v[182:183], off
	v_lshl_add_u64 v[182:183], v[230:231], 0, s[40:41]
	s_mov_b32 m0, s53
	s_nop 0
	global_load_lds_dwordx4 v[182:183], off
	v_lshl_add_u64 v[182:183], v[232:233], 0, s[40:41]
	s_mov_b32 m0, s64
	s_nop 0
	global_load_lds_dwordx4 v[182:183], off
	s_waitcnt vmcnt(8)
	s_waitcnt lgkmcnt(0)
	s_barrier
	s_setprio 1
	s_waitcnt lgkmcnt(0)
	v_mfma_f32_16x16x32_bf16 v[60:63], v[150:153], v[186:189], v[60:63]
	v_mfma_f32_16x16x32_bf16 v[56:59], v[158:161], v[186:189], v[56:59]
	v_mfma_f32_16x16x32_bf16 v[44:47], v[150:153], v[194:197], v[44:47]
	v_mfma_f32_16x16x32_bf16 v[40:43], v[158:161], v[194:197], v[40:43]
	v_mfma_f32_16x16x32_bf16 v[28:31], v[150:153], v[202:205], v[28:31]
	v_mfma_f32_16x16x32_bf16 v[24:27], v[158:161], v[202:205], v[24:27]
	v_mfma_f32_16x16x32_bf16 v[12:15], v[150:153], v[210:213], v[12:15]
	v_mfma_f32_16x16x32_bf16 v[8:11], v[158:161], v[210:213], v[8:11]
	v_mfma_f32_16x16x32_bf16 v[60:63], v[154:157], v[190:193], v[60:63]
	v_mfma_f32_16x16x32_bf16 v[56:59], v[162:165], v[190:193], v[56:59]
	v_mfma_f32_16x16x32_bf16 v[44:47], v[154:157], v[198:201], v[44:47]
	v_mfma_f32_16x16x32_bf16 v[40:43], v[162:165], v[198:201], v[40:43]
	v_mfma_f32_16x16x32_bf16 v[28:31], v[154:157], v[206:209], v[28:31]
	v_mfma_f32_16x16x32_bf16 v[24:27], v[162:165], v[206:209], v[24:27]
	v_mfma_f32_16x16x32_bf16 v[12:15], v[154:157], v[214:217], v[12:15]
	v_mfma_f32_16x16x32_bf16 v[8:11], v[162:165], v[214:217], v[8:11]
	s_setprio 0
	s_setprio 1
	v_mfma_f32_16x16x32_bf16 v[52:55], v[166:169], v[186:189], v[52:55]
	v_mfma_f32_16x16x32_bf16 v[48:51], v[174:177], v[186:189], v[48:51]
	v_mfma_f32_16x16x32_bf16 v[36:39], v[166:169], v[194:197], v[36:39]
	v_mfma_f32_16x16x32_bf16 v[32:35], v[174:177], v[194:197], v[32:35]
	v_mfma_f32_16x16x32_bf16 v[20:23], v[166:169], v[202:205], v[20:23]
	v_mfma_f32_16x16x32_bf16 v[16:19], v[174:177], v[202:205], v[16:19]
	v_mfma_f32_16x16x32_bf16 v[4:7], v[166:169], v[210:213], v[4:7]
	v_mfma_f32_16x16x32_bf16 v[0:3], v[174:177], v[210:213], v[0:3]
	v_mfma_f32_16x16x32_bf16 v[52:55], v[170:173], v[190:193], v[52:55]
	v_mfma_f32_16x16x32_bf16 v[48:51], v[178:181], v[190:193], v[48:51]
	v_mfma_f32_16x16x32_bf16 v[36:39], v[170:173], v[198:201], v[36:39]
	v_mfma_f32_16x16x32_bf16 v[32:35], v[178:181], v[198:201], v[32:35]
	v_mfma_f32_16x16x32_bf16 v[20:23], v[170:173], v[206:209], v[20:23]
	v_mfma_f32_16x16x32_bf16 v[16:19], v[178:181], v[206:209], v[16:19]
	v_mfma_f32_16x16x32_bf16 v[4:7], v[170:173], v[214:217], v[4:7]
	v_mfma_f32_16x16x32_bf16 v[0:3], v[178:181], v[214:217], v[0:3]
	s_setprio 0
	s_barrier
	s_add_u32 s58, s58, 0x100
	s_addc_u32 s59, s59, 0
	s_add_u32 s71, s71, 0x100
	s_addc_u32 s78, s78, 0
	s_cmp_ge_i32 s79, s49
	s_mov_b32 s60, s79
	s_cbranch_scc0 .LBB0_679
	v_readlane_b32 s82, v248, 38
	v_readlane_b32 s83, v248, 39
	s_branch .LBB0_681
.Lzx679:
	v_mov_b32_e32 v123, 0
	v_mov_b32_e32 v122, v123
	v_mov_b32_e32 v121, v123
	v_mov_b32_e32 v120, v123
	v_mov_b32_e32 v127, v123
	v_mov_b32_e32 v126, v123
	v_mov_b32_e32 v125, v123
	v_mov_b32_e32 v124, v123
	v_mov_b32_e32 v111, v123
	v_mov_b32_e32 v110, v123
	v_mov_b32_e32 v109, v123
	v_mov_b32_e32 v108, v123
	v_mov_b32_e32 v107, v123
	v_mov_b32_e32 v106, v123
	v_mov_b32_e32 v105, v123
	v_mov_b32_e32 v104, v123
	v_mov_b32_e32 v95, v123
	v_mov_b32_e32 v94, v123
	v_mov_b32_e32 v93, v123
	v_mov_b32_e32 v92, v123
	v_mov_b32_e32 v91, v123
	v_mov_b32_e32 v90, v123
	v_mov_b32_e32 v89, v123
	v_mov_b32_e32 v88, v123
	v_mov_b32_e32 v79, v123
	v_mov_b32_e32 v78, v123
	v_mov_b32_e32 v77, v123
	v_mov_b32_e32 v76, v123
	v_mov_b32_e32 v75, v123
	v_mov_b32_e32 v74, v123
	v_mov_b32_e32 v73, v123
	v_mov_b32_e32 v72, v123
	v_mov_b32_e32 v119, v123
	v_mov_b32_e32 v118, v123
	v_mov_b32_e32 v117, v123
	v_mov_b32_e32 v116, v123
	v_mov_b32_e32 v115, v123
	v_mov_b32_e32 v114, v123
	v_mov_b32_e32 v113, v123
	v_mov_b32_e32 v112, v123
	v_mov_b32_e32 v103, v123
	v_mov_b32_e32 v102, v123
	v_mov_b32_e32 v101, v123
	v_mov_b32_e32 v100, v123
	v_mov_b32_e32 v99, v123
	v_mov_b32_e32 v98, v123
	v_mov_b32_e32 v97, v123
	v_mov_b32_e32 v96, v123
	v_mov_b32_e32 v87, v123
	v_mov_b32_e32 v86, v123
	v_mov_b32_e32 v85, v123
	v_mov_b32_e32 v84, v123
	v_mov_b32_e32 v83, v123
	v_mov_b32_e32 v82, v123
	v_mov_b32_e32 v81, v123
	v_mov_b32_e32 v80, v123
	v_mov_b32_e32 v71, v123
	v_mov_b32_e32 v70, v123
	v_mov_b32_e32 v69, v123
	v_mov_b32_e32 v68, v123
	v_mov_b32_e32 v67, v123
	v_mov_b32_e32 v66, v123
	v_mov_b32_e32 v65, v123
	v_mov_b32_e32 v64, v123
	v_mov_b32_e32 v63, v123
	v_mov_b32_e32 v62, v123
	v_mov_b32_e32 v61, v123
	v_mov_b32_e32 v60, v123
	v_mov_b32_e32 v59, v123
	v_mov_b32_e32 v58, v123
	v_mov_b32_e32 v57, v123
	v_mov_b32_e32 v56, v123
	v_mov_b32_e32 v47, v123
	v_mov_b32_e32 v46, v123
	v_mov_b32_e32 v45, v123
	v_mov_b32_e32 v44, v123
	v_mov_b32_e32 v43, v123
	v_mov_b32_e32 v42, v123
	v_mov_b32_e32 v41, v123
	v_mov_b32_e32 v40, v123
	v_mov_b32_e32 v31, v123
	v_mov_b32_e32 v30, v123
	v_mov_b32_e32 v29, v123
	v_mov_b32_e32 v28, v123
	v_mov_b32_e32 v27, v123
	v_mov_b32_e32 v26, v123
	v_mov_b32_e32 v25, v123
	v_mov_b32_e32 v24, v123
	v_mov_b32_e32 v15, v123
	v_mov_b32_e32 v14, v123
	v_mov_b32_e32 v13, v123
	v_mov_b32_e32 v12, v123
	v_mov_b32_e32 v11, v123
	v_mov_b32_e32 v10, v123
	v_mov_b32_e32 v9, v123
	v_mov_b32_e32 v8, v123
	v_mov_b32_e32 v55, v123
	v_mov_b32_e32 v54, v123
	v_mov_b32_e32 v53, v123
	v_mov_b32_e32 v52, v123
	v_mov_b32_e32 v51, v123
	v_mov_b32_e32 v50, v123
	v_mov_b32_e32 v49, v123
	v_mov_b32_e32 v48, v123
	v_mov_b32_e32 v39, v123
	v_mov_b32_e32 v38, v123
	v_mov_b32_e32 v37, v123
	v_mov_b32_e32 v36, v123
	v_mov_b32_e32 v35, v123
	v_mov_b32_e32 v34, v123
	v_mov_b32_e32 v33, v123
	v_mov_b32_e32 v32, v123
	v_mov_b32_e32 v23, v123
	v_mov_b32_e32 v22, v123
	v_mov_b32_e32 v21, v123
	v_mov_b32_e32 v20, v123
	v_mov_b32_e32 v19, v123
	v_mov_b32_e32 v18, v123
	v_mov_b32_e32 v17, v123
	v_mov_b32_e32 v16, v123
	v_mov_b32_e32 v7, v123
	v_mov_b32_e32 v6, v123
	v_mov_b32_e32 v5, v123
	v_mov_b32_e32 v4, v123
	v_mov_b32_e32 v3, v123
	v_mov_b32_e32 v2, v123
	v_mov_b32_e32 v1, v123
	v_mov_b32_e32 v0, v123

.LBB0_919:
	s_and_b64 vcc, exec, s[8:9]
	s_cbranch_vccnz .Lzx921
	s_add_u32 s40, s40, 0x80
	s_addc_u32 s41, s41, 0
	s_add_u32 s61, s42, 0x100
	v_mov_b32_e32 v0, 0
	s_addc_u32 s62, s43, 0
	s_mov_b32 s42, 0
	v_mov_b32_e32 v1, v0
	v_mov_b32_e32 v2, v0
	v_mov_b32_e32 v3, v0
	v_mov_b32_e32 v8, v0
	v_mov_b32_e32 v9, v0
	v_mov_b32_e32 v10, v0
	v_mov_b32_e32 v11, v0
	v_mov_b32_e32 v16, v0
	v_mov_b32_e32 v17, v0
	v_mov_b32_e32 v18, v0
	v_mov_b32_e32 v19, v0
	v_mov_b32_e32 v24, v0
	v_mov_b32_e32 v25, v0
	v_mov_b32_e32 v26, v0
	v_mov_b32_e32 v27, v0
	v_mov_b32_e32 v32, v0
	v_mov_b32_e32 v33, v0
	v_mov_b32_e32 v34, v0
	v_mov_b32_e32 v35, v0
	v_mov_b32_e32 v40, v0
	v_mov_b32_e32 v41, v0
	v_mov_b32_e32 v42, v0
	v_mov_b32_e32 v43, v0
	v_mov_b32_e32 v48, v0
	v_mov_b32_e32 v49, v0
	v_mov_b32_e32 v50, v0
	v_mov_b32_e32 v51, v0
	v_mov_b32_e32 v56, v0
	v_mov_b32_e32 v57, v0
	v_mov_b32_e32 v58, v0
	v_mov_b32_e32 v59, v0
	v_mov_b32_e32 v4, v0
	v_mov_b32_e32 v5, v0
	v_mov_b32_e32 v6, v0
	v_mov_b32_e32 v7, v0
	v_mov_b32_e32 v12, v0
	v_mov_b32_e32 v13, v0
	v_mov_b32_e32 v14, v0
	v_mov_b32_e32 v15, v0
	v_mov_b32_e32 v20, v0
	v_mov_b32_e32 v21, v0
	v_mov_b32_e32 v22, v0
	v_mov_b32_e32 v23, v0
	v_mov_b32_e32 v28, v0
	v_mov_b32_e32 v29, v0
	v_mov_b32_e32 v30, v0
	v_mov_b32_e32 v31, v0
	v_mov_b32_e32 v36, v0
	v_mov_b32_e32 v37, v0
	v_mov_b32_e32 v38, v0
	v_mov_b32_e32 v39, v0
	v_mov_b32_e32 v44, v0
	v_mov_b32_e32 v45, v0
	v_mov_b32_e32 v46, v0
	v_mov_b32_e32 v47, v0
	v_mov_b32_e32 v52, v0
	v_mov_b32_e32 v53, v0
	v_mov_b32_e32 v54, v0
	v_mov_b32_e32 v55, v0
	v_mov_b32_e32 v60, v0
	v_mov_b32_e32 v61, v0
	v_mov_b32_e32 v62, v0
	v_mov_b32_e32 v63, v0
	v_mov_b32_e32 v64, v0
	v_mov_b32_e32 v65, v0
	v_mov_b32_e32 v66, v0
	v_mov_b32_e32 v67, v0
	v_mov_b32_e32 v72, v0
	v_mov_b32_e32 v73, v0
	v_mov_b32_e32 v74, v0
	v_mov_b32_e32 v75, v0
	v_mov_b32_e32 v80, v0
	v_mov_b32_e32 v81, v0
	v_mov_b32_e32 v82, v0
	v_mov_b32_e32 v83, v0
	v_mov_b32_e32 v88, v0
	v_mov_b32_e32 v89, v0
	v_mov_b32_e32 v90, v0
	v_mov_b32_e32 v91, v0
	v_mov_b32_e32 v96, v0
	v_mov_b32_e32 v97, v0
	v_mov_b32_e32 v98, v0
	v_mov_b32_e32 v99, v0
	v_mov_b32_e32 v104, v0
	v_mov_b32_e32 v105, v0
	v_mov_b32_e32 v106, v0
	v_mov_b32_e32 v107, v0
	v_mov_b32_e32 v112, v0
	v_mov_b32_e32 v113, v0
	v_mov_b32_e32 v114, v0
	v_mov_b32_e32 v115, v0
	v_mov_b32_e32 v124, v0
	v_mov_b32_e32 v125, v0
	v_mov_b32_e32 v126, v0
	v_mov_b32_e32 v127, v0
	v_mov_b32_e32 v68, v0
	v_mov_b32_e32 v69, v0
	v_mov_b32_e32 v70, v0
	v_mov_b32_e32 v71, v0
	v_mov_b32_e32 v76, v0
	v_mov_b32_e32 v77, v0
	v_mov_b32_e32 v78, v0
	v_mov_b32_e32 v79, v0
	v_mov_b32_e32 v84, v0
	v_mov_b32_e32 v85, v0
	v_mov_b32_e32 v86, v0
	v_mov_b32_e32 v87, v0
	v_mov_b32_e32 v92, v0
	v_mov_b32_e32 v93, v0
	v_mov_b32_e32 v94, v0
	v_mov_b32_e32 v95, v0
	v_mov_b32_e32 v100, v0
	v_mov_b32_e32 v101, v0
	v_mov_b32_e32 v102, v0
	v_mov_b32_e32 v103, v0
	v_mov_b32_e32 v108, v0
	v_mov_b32_e32 v109, v0
	v_mov_b32_e32 v110, v0
	v_mov_b32_e32 v111, v0
	v_mov_b32_e32 v116, v0
	v_mov_b32_e32 v117, v0
	v_mov_b32_e32 v118, v0
	v_mov_b32_e32 v119, v0
	v_mov_b32_e32 v120, v0
	v_mov_b32_e32 v121, v0
	v_mov_b32_e32 v122, v0
	v_mov_b32_e32 v123, v0
.LBB0_921:
	ds_read_b128 v[144:147], v153
	ds_read_b128 v[158:161], v153 offset:1024
	ds_read_b128 v[162:165], v153 offset:2048
	ds_read_b128 v[166:169], v153 offset:3072
	ds_read_b128 v[170:173], v154
	ds_read_b128 v[174:177], v154 offset:1024
	ds_read_b128 v[178:181], v154 offset:2048
	ds_read_b128 v[186:189], v154 offset:3072
	s_add_i32 s63, s42, 2
	s_add_u32 s64, s40, 0x80
	s_addc_u32 s43, s41, 0
	s_cmp_eq_u32 s50, s42
	s_cselect_b32 s42, s6, s64
	s_cselect_b32 s43, s7, s43
	s_cselect_b32 s65, s39, s62
	s_cselect_b32 s64, s38, s61
	s_mov_b32 m0, s53
	v_lshl_add_u64 v[148:149], s[40:41], 0, v[136:137]
	ds_read_b128 v[190:193], v155
	ds_read_b128 v[194:197], v155 offset:1024
	ds_read_b128 v[198:201], v155 offset:2048
	ds_read_b128 v[202:205], v155 offset:3072
	ds_read_b128 v[206:209], v155 offset:4096
	ds_read_b128 v[210:213], v155 offset:5120
	ds_read_b128 v[214:217], v155 offset:6144
	ds_read_b128 v[224:227], v155 offset:7168
	global_load_lds_dwordx4 v[148:149], off
	v_lshl_add_u64 v[148:149], s[40:41], 0, v[138:139]
	s_mov_b32 m0, s54
	s_nop 0
	global_load_lds_dwordx4 v[148:149], off
	s_waitcnt vmcnt(8)
	s_waitcnt lgkmcnt(0)
	s_barrier
	s_setprio 1
	s_waitcnt lgkmcnt(0)
	v_mfma_f32_16x16x32_bf16 v[120:123], v[144:147], v[190:193], v[120:123]
	v_mfma_f32_16x16x32_bf16 v[116:119], v[162:165], v[190:193], v[116:119]
	v_mfma_f32_16x16x32_bf16 v[108:111], v[144:147], v[198:201], v[108:111]
	v_mfma_f32_16x16x32_bf16 v[100:103], v[162:165], v[198:201], v[100:103]
	v_mfma_f32_16x16x32_bf16 v[92:95], v[144:147], v[206:209], v[92:95]
	v_mfma_f32_16x16x32_bf16 v[84:87], v[162:165], v[206:209], v[84:87]
	v_mfma_f32_16x16x32_bf16 v[76:79], v[144:147], v[214:217], v[76:79]
	v_mfma_f32_16x16x32_bf16 v[68:71], v[162:165], v[214:217], v[68:71]
	v_mfma_f32_16x16x32_bf16 v[120:123], v[158:161], v[194:197], v[120:123]
	v_mfma_f32_16x16x32_bf16 v[116:119], v[166:169], v[194:197], v[116:119]
	v_mfma_f32_16x16x32_bf16 v[108:111], v[158:161], v[202:205], v[108:111]
	v_mfma_f32_16x16x32_bf16 v[100:103], v[166:169], v[202:205], v[100:103]
	v_mfma_f32_16x16x32_bf16 v[92:95], v[158:161], v[210:213], v[92:95]
	v_mfma_f32_16x16x32_bf16 v[84:87], v[166:169], v[210:213], v[84:87]
	v_mfma_f32_16x16x32_bf16 v[76:79], v[158:161], v[224:227], v[76:79]
	v_mfma_f32_16x16x32_bf16 v[68:71], v[166:169], v[224:227], v[68:71]
	s_setprio 0
	s_setprio 1
	v_mfma_f32_16x16x32_bf16 v[124:127], v[170:173], v[190:193], v[124:127]
	v_mfma_f32_16x16x32_bf16 v[112:115], v[178:181], v[190:193], v[112:115]
	v_mfma_f32_16x16x32_bf16 v[104:107], v[170:173], v[198:201], v[104:107]
	v_mfma_f32_16x16x32_bf16 v[96:99], v[178:181], v[198:201], v[96:99]
	v_mfma_f32_16x16x32_bf16 v[88:91], v[170:173], v[206:209], v[88:91]
	v_mfma_f32_16x16x32_bf16 v[80:83], v[178:181], v[206:209], v[80:83]
	v_mfma_f32_16x16x32_bf16 v[72:75], v[170:173], v[214:217], v[72:75]
	v_mfma_f32_16x16x32_bf16 v[64:67], v[178:181], v[214:217], v[64:67]
	v_mfma_f32_16x16x32_bf16 v[124:127], v[174:177], v[194:197], v[124:127]
	v_mfma_f32_16x16x32_bf16 v[112:115], v[186:189], v[194:197], v[112:115]
	v_mfma_f32_16x16x32_bf16 v[104:107], v[174:177], v[202:205], v[104:107]
	v_mfma_f32_16x16x32_bf16 v[96:99], v[186:189], v[202:205], v[96:99]
	v_mfma_f32_16x16x32_bf16 v[88:91], v[174:177], v[210:213], v[88:91]
	v_mfma_f32_16x16x32_bf16 v[80:83], v[186:189], v[210:213], v[80:83]
	v_mfma_f32_16x16x32_bf16 v[72:75], v[174:177], v[224:227], v[72:75]
	v_mfma_f32_16x16x32_bf16 v[64:67], v[186:189], v[224:227], v[64:67]
	s_setprio 0
	s_barrier
	s_mov_b32 m0, s55
	v_lshl_add_u64 v[148:149], s[64:65], 0, v[132:133]
	v_lshl_add_u64 v[182:183], s[64:65], 0, v[128:129]
	s_add_u32 s64, s64, s16
	ds_read_b128 v[190:193], v155 offset:16384
	ds_read_b128 v[194:197], v155 offset:17408
	ds_read_b128 v[198:201], v155 offset:18432
	ds_read_b128 v[202:205], v155 offset:19456
	ds_read_b128 v[206:209], v155 offset:20480
	ds_read_b128 v[210:213], v155 offset:21504
	ds_read_b128 v[214:217], v155 offset:22528
	ds_read_b128 v[224:227], v155 offset:23552
	global_load_lds_dwordx4 v[148:149], off
	s_mov_b32 m0, s56
	s_addc_u32 s65, s65, s17
	s_add_i32 s66, s51, s31
	global_load_lds_dwordx4 v[182:183], off
	v_lshl_add_u64 v[228:229], s[64:65], 0, v[132:133]
	s_mov_b32 m0, s66
	v_lshl_add_u64 v[230:231], s[64:65], 0, v[128:129]
	global_load_lds_dwordx4 v[228:229], off
	s_add_i32 m0, s66, 0x2000
	v_lshl_add_u64 v[232:233], s[42:43], 0, v[134:135]
	global_load_lds_dwordx4 v[230:231], off
	s_mov_b32 m0, s28
	v_lshl_add_u64 v[234:235], s[42:43], 0, v[130:131]
	global_load_lds_dwordx4 v[232:233], off
	s_mov_b32 m0, s33
	s_nop 0
	global_load_lds_dwordx4 v[234:235], off
	s_waitcnt vmcnt(8)
	s_waitcnt lgkmcnt(0)
	s_barrier
	s_setprio 1
	s_waitcnt lgkmcnt(0)
	v_mfma_f32_16x16x32_bf16 v[60:63], v[144:147], v[190:193], v[60:63]
	v_mfma_f32_16x16x32_bf16 v[52:55], v[162:165], v[190:193], v[52:55]
	v_mfma_f32_16x16x32_bf16 v[44:47], v[144:147], v[198:201], v[44:47]
	v_mfma_f32_16x16x32_bf16 v[36:39], v[162:165], v[198:201], v[36:39]
	v_mfma_f32_16x16x32_bf16 v[28:31], v[144:147], v[206:209], v[28:31]
	v_mfma_f32_16x16x32_bf16 v[20:23], v[162:165], v[206:209], v[20:23]
	v_mfma_f32_16x16x32_bf16 v[12:15], v[144:147], v[214:217], v[12:15]
	v_mfma_f32_16x16x32_bf16 v[4:7], v[162:165], v[214:217], v[4:7]
	v_mfma_f32_16x16x32_bf16 v[60:63], v[158:161], v[194:197], v[60:63]
	v_mfma_f32_16x16x32_bf16 v[52:55], v[166:169], v[194:197], v[52:55]
	v_mfma_f32_16x16x32_bf16 v[44:47], v[158:161], v[202:205], v[44:47]
	v_mfma_f32_16x16x32_bf16 v[36:39], v[166:169], v[202:205], v[36:39]
	v_mfma_f32_16x16x32_bf16 v[28:31], v[158:161], v[210:213], v[28:31]
	v_mfma_f32_16x16x32_bf16 v[20:23], v[166:169], v[210:213], v[20:23]
	v_mfma_f32_16x16x32_bf16 v[12:15], v[158:161], v[224:227], v[12:15]
	v_mfma_f32_16x16x32_bf16 v[4:7], v[166:169], v[224:227], v[4:7]
	s_setprio 0
	s_setprio 1
	v_mfma_f32_16x16x32_bf16 v[56:59], v[170:173], v[190:193], v[56:59]
	v_mfma_f32_16x16x32_bf16 v[48:51], v[178:181], v[190:193], v[48:51]
	v_mfma_f32_16x16x32_bf16 v[40:43], v[170:173], v[198:201], v[40:43]
	v_mfma_f32_16x16x32_bf16 v[32:35], v[178:181], v[198:201], v[32:35]
	v_mfma_f32_16x16x32_bf16 v[24:27], v[170:173], v[206:209], v[24:27]
	v_mfma_f32_16x16x32_bf16 v[16:19], v[178:181], v[206:209], v[16:19]
	v_mfma_f32_16x16x32_bf16 v[8:11], v[170:173], v[214:217], v[8:11]
	v_mfma_f32_16x16x32_bf16 v[0:3], v[178:181], v[214:217], v[0:3]
	v_mfma_f32_16x16x32_bf16 v[56:59], v[174:177], v[194:197], v[56:59]
	v_mfma_f32_16x16x32_bf16 v[48:51], v[186:189], v[194:197], v[48:51]
	v_mfma_f32_16x16x32_bf16 v[40:43], v[174:177], v[202:205], v[40:43]
	v_mfma_f32_16x16x32_bf16 v[32:35], v[186:189], v[202:205], v[32:35]
	v_mfma_f32_16x16x32_bf16 v[24:27], v[174:177], v[210:213], v[24:27]
	v_mfma_f32_16x16x32_bf16 v[16:19], v[186:189], v[210:213], v[16:19]
	v_mfma_f32_16x16x32_bf16 v[8:11], v[174:177], v[224:227], v[8:11]
	v_mfma_f32_16x16x32_bf16 v[0:3], v[186:189], v[224:227], v[0:3]
	s_setprio 0
	s_barrier
	s_add_i32 s64, 0, 0x18000
	v_add_u32_e32 v157, s64, v151
	s_add_i32 s65, 0, 0x1c000
	ds_read_b128 v[144:147], v157
	ds_read_b128 v[158:161], v157 offset:1024
	ds_read_b128 v[162:165], v157 offset:2048
	ds_read_b128 v[166:169], v157 offset:3072
	v_add_u32_e32 v157, s65, v151
	ds_read_b128 v[170:173], v157
	ds_read_b128 v[174:177], v157 offset:1024
	ds_read_b128 v[178:181], v157 offset:2048
	ds_read_b128 v[186:189], v157 offset:3072
	s_add_u32 s42, s42, s16
	s_addc_u32 s43, s43, s17
	s_mov_b32 m0, s44
	v_lshl_add_u64 v[236:237], s[42:43], 0, v[134:135]
	ds_read_b128 v[190:193], v155 offset:32768
	ds_read_b128 v[194:197], v155 offset:33792
	ds_read_b128 v[198:201], v155 offset:34816
	ds_read_b128 v[202:205], v155 offset:35840
	ds_read_b128 v[206:209], v155 offset:36864
	ds_read_b128 v[210:213], v155 offset:37888
	ds_read_b128 v[214:217], v155 offset:38912
	ds_read_b128 v[224:227], v155 offset:39936
	global_load_lds_dwordx4 v[236:237], off
	v_lshl_add_u64 v[236:237], s[42:43], 0, v[130:131]
	s_mov_b32 m0, s45
	s_nop 0
	global_load_lds_dwordx4 v[236:237], off
	s_waitcnt vmcnt(8)
	s_waitcnt lgkmcnt(0)
	s_barrier
	s_setprio 1
	s_waitcnt lgkmcnt(0)
	v_mfma_f32_16x16x32_bf16 v[120:123], v[144:147], v[190:193], v[120:123]
	v_mfma_f32_16x16x32_bf16 v[116:119], v[162:165], v[190:193], v[116:119]
	v_mfma_f32_16x16x32_bf16 v[108:111], v[144:147], v[198:201], v[108:111]
	v_mfma_f32_16x16x32_bf16 v[100:103], v[162:165], v[198:201], v[100:103]
	v_mfma_f32_16x16x32_bf16 v[92:95], v[144:147], v[206:209], v[92:95]
	v_mfma_f32_16x16x32_bf16 v[84:87], v[162:165], v[206:209], v[84:87]
	v_mfma_f32_16x16x32_bf16 v[76:79], v[144:147], v[214:217], v[76:79]
	v_mfma_f32_16x16x32_bf16 v[68:71], v[162:165], v[214:217], v[68:71]
	v_mfma_f32_16x16x32_bf16 v[120:123], v[158:161], v[194:197], v[120:123]
	v_mfma_f32_16x16x32_bf16 v[116:119], v[166:169], v[194:197], v[116:119]
	v_mfma_f32_16x16x32_bf16 v[108:111], v[158:161], v[202:205], v[108:111]
	v_mfma_f32_16x16x32_bf16 v[100:103], v[166:169], v[202:205], v[100:103]
	v_mfma_f32_16x16x32_bf16 v[92:95], v[158:161], v[210:213], v[92:95]
	v_mfma_f32_16x16x32_bf16 v[84:87], v[166:169], v[210:213], v[84:87]
	v_mfma_f32_16x16x32_bf16 v[76:79], v[158:161], v[224:227], v[76:79]
	v_mfma_f32_16x16x32_bf16 v[68:71], v[166:169], v[224:227], v[68:71]
	s_setprio 0
	s_setprio 1
	v_mfma_f32_16x16x32_bf16 v[124:127], v[170:173], v[190:193], v[124:127]
	v_mfma_f32_16x16x32_bf16 v[112:115], v[178:181], v[190:193], v[112:115]
	v_mfma_f32_16x16x32_bf16 v[104:107], v[170:173], v[198:201], v[104:107]
	v_mfma_f32_16x16x32_bf16 v[96:99], v[178:181], v[198:201], v[96:99]
	v_mfma_f32_16x16x32_bf16 v[88:91], v[170:173], v[206:209], v[88:91]
	v_mfma_f32_16x16x32_bf16 v[80:83], v[178:181], v[206:209], v[80:83]
	v_mfma_f32_16x16x32_bf16 v[72:75], v[170:173], v[214:217], v[72:75]
	v_mfma_f32_16x16x32_bf16 v[64:67], v[178:181], v[214:217], v[64:67]
	v_mfma_f32_16x16x32_bf16 v[124:127], v[174:177], v[194:197], v[124:127]
	v_mfma_f32_16x16x32_bf16 v[112:115], v[186:189], v[194:197], v[112:115]
	v_mfma_f32_16x16x32_bf16 v[104:107], v[174:177], v[202:205], v[104:107]
	v_mfma_f32_16x16x32_bf16 v[96:99], v[186:189], v[202:205], v[96:99]
	v_mfma_f32_16x16x32_bf16 v[88:91], v[174:177], v[210:213], v[88:91]
	v_mfma_f32_16x16x32_bf16 v[80:83], v[186:189], v[210:213], v[80:83]
	v_mfma_f32_16x16x32_bf16 v[72:75], v[174:177], v[224:227], v[72:75]
	v_mfma_f32_16x16x32_bf16 v[64:67], v[186:189], v[224:227], v[64:67]
	s_setprio 0
	s_barrier
	s_add_i32 s42, s64, s31
	v_lshl_add_u64 v[148:149], v[148:149], 0, s[36:37]
	s_mov_b32 m0, s42
	ds_read_b128 v[190:193], v155 offset:49152
	ds_read_b128 v[194:197], v155 offset:50176
	ds_read_b128 v[198:201], v155 offset:51200
	ds_read_b128 v[202:205], v155 offset:52224
	ds_read_b128 v[206:209], v155 offset:53248
	ds_read_b128 v[210:213], v155 offset:54272
	ds_read_b128 v[214:217], v155 offset:55296
	ds_read_b128 v[224:227], v155 offset:56320
	global_load_lds_dwordx4 v[148:149], off
	v_lshl_add_u64 v[148:149], v[182:183], 0, s[36:37]
	s_add_i32 m0, s42, 0x2000
	s_add_i32 s42, s65, s31
	global_load_lds_dwordx4 v[148:149], off
	v_lshl_add_u64 v[148:149], v[228:229], 0, s[36:37]
	s_mov_b32 m0, s42
	s_nop 0
	global_load_lds_dwordx4 v[148:149], off
	v_lshl_add_u64 v[148:149], v[230:231], 0, s[36:37]
	s_add_i32 m0, s42, 0x2000
	s_nop 0
	global_load_lds_dwordx4 v[148:149], off
	v_lshl_add_u64 v[148:149], v[232:233], 0, s[36:37]
	s_mov_b32 m0, s47
	s_nop 0
	global_load_lds_dwordx4 v[148:149], off
	v_lshl_add_u64 v[148:149], v[234:235], 0, s[36:37]
	s_mov_b32 m0, s48
	s_nop 0
	global_load_lds_dwordx4 v[148:149], off
	s_waitcnt vmcnt(8)
	s_waitcnt lgkmcnt(0)
	s_barrier
	s_setprio 1
	s_waitcnt lgkmcnt(0)
	v_mfma_f32_16x16x32_bf16 v[60:63], v[144:147], v[190:193], v[60:63]
	v_mfma_f32_16x16x32_bf16 v[52:55], v[162:165], v[190:193], v[52:55]
	v_mfma_f32_16x16x32_bf16 v[44:47], v[144:147], v[198:201], v[44:47]
	v_mfma_f32_16x16x32_bf16 v[36:39], v[162:165], v[198:201], v[36:39]
	v_mfma_f32_16x16x32_bf16 v[28:31], v[144:147], v[206:209], v[28:31]
	v_mfma_f32_16x16x32_bf16 v[20:23], v[162:165], v[206:209], v[20:23]
	v_mfma_f32_16x16x32_bf16 v[12:15], v[144:147], v[214:217], v[12:15]
	v_mfma_f32_16x16x32_bf16 v[4:7], v[162:165], v[214:217], v[4:7]
	v_mfma_f32_16x16x32_bf16 v[60:63], v[158:161], v[194:197], v[60:63]
	v_mfma_f32_16x16x32_bf16 v[52:55], v[166:169], v[194:197], v[52:55]
	v_mfma_f32_16x16x32_bf16 v[44:47], v[158:161], v[202:205], v[44:47]
	v_mfma_f32_16x16x32_bf16 v[36:39], v[166:169], v[202:205], v[36:39]
	v_mfma_f32_16x16x32_bf16 v[28:31], v[158:161], v[210:213], v[28:31]
	v_mfma_f32_16x16x32_bf16 v[20:23], v[166:169], v[210:213], v[20:23]
	v_mfma_f32_16x16x32_bf16 v[12:15], v[158:161], v[224:227], v[12:15]
	v_mfma_f32_16x16x32_bf16 v[4:7], v[166:169], v[224:227], v[4:7]
	s_setprio 0
	s_setprio 1
	v_mfma_f32_16x16x32_bf16 v[56:59], v[170:173], v[190:193], v[56:59]
	v_mfma_f32_16x16x32_bf16 v[48:51], v[178:181], v[190:193], v[48:51]
	v_mfma_f32_16x16x32_bf16 v[40:43], v[170:173], v[198:201], v[40:43]
	v_mfma_f32_16x16x32_bf16 v[32:35], v[178:181], v[198:201], v[32:35]
	v_mfma_f32_16x16x32_bf16 v[24:27], v[170:173], v[206:209], v[24:27]
	v_mfma_f32_16x16x32_bf16 v[16:19], v[178:181], v[206:209], v[16:19]
	v_mfma_f32_16x16x32_bf16 v[8:11], v[170:173], v[214:217], v[8:11]
	v_mfma_f32_16x16x32_bf16 v[0:3], v[178:181], v[214:217], v[0:3]
	v_mfma_f32_16x16x32_bf16 v[56:59], v[174:177], v[194:197], v[56:59]
	v_mfma_f32_16x16x32_bf16 v[48:51], v[186:189], v[194:197], v[48:51]
	v_mfma_f32_16x16x32_bf16 v[40:43], v[174:177], v[202:205], v[40:43]
	v_mfma_f32_16x16x32_bf16 v[32:35], v[186:189], v[202:205], v[32:35]
	v_mfma_f32_16x16x32_bf16 v[24:27], v[174:177], v[210:213], v[24:27]
	v_mfma_f32_16x16x32_bf16 v[16:19], v[186:189], v[210:213], v[16:19]
	v_mfma_f32_16x16x32_bf16 v[8:11], v[174:177], v[224:227], v[8:11]
	v_mfma_f32_16x16x32_bf16 v[0:3], v[186:189], v[224:227], v[0:3]
	s_setprio 0
	s_barrier
	s_add_u32 s40, s40, 0x100
	s_addc_u32 s41, s41, 0
	s_add_u32 s61, s61, 0x100
	s_addc_u32 s62, s62, 0
	s_cmp_ge_i32 s63, s49
	s_mov_b32 s42, s63
	s_cbranch_scc0 .LBB0_921
	s_branch .LBB0_922
.Lzx921:
	v_mov_b32_e32 v123, 0
	v_mov_b32_e32 v122, v123
	v_mov_b32_e32 v121, v123
	v_mov_b32_e32 v120, v123
	v_mov_b32_e32 v119, v123
	v_mov_b32_e32 v118, v123
	v_mov_b32_e32 v117, v123
	v_mov_b32_e32 v116, v123
	v_mov_b32_e32 v111, v123
	v_mov_b32_e32 v110, v123
	v_mov_b32_e32 v109, v123
	v_mov_b32_e32 v108, v123
	v_mov_b32_e32 v103, v123
	v_mov_b32_e32 v102, v123
	v_mov_b32_e32 v101, v123
	v_mov_b32_e32 v100, v123
	v_mov_b32_e32 v95, v123
	v_mov_b32_e32 v94, v123
	v_mov_b32_e32 v93, v123
	v_mov_b32_e32 v92, v123
	v_mov_b32_e32 v87, v123
	v_mov_b32_e32 v86, v123
	v_mov_b32_e32 v85, v123
	v_mov_b32_e32 v84, v123
	v_mov_b32_e32 v79, v123
	v_mov_b32_e32 v78, v123
	v_mov_b32_e32 v77, v123
	v_mov_b32_e32 v76, v123
	v_mov_b32_e32 v71, v123
	v_mov_b32_e32 v70, v123
	v_mov_b32_e32 v69, v123
	v_mov_b32_e32 v68, v123
	v_mov_b32_e32 v127, v123
	v_mov_b32_e32 v126, v123
	v_mov_b32_e32 v125, v123
	v_mov_b32_e32 v124, v123
	v_mov_b32_e32 v115, v123
	v_mov_b32_e32 v114, v123
	v_mov_b32_e32 v113, v123
	v_mov_b32_e32 v112, v123
	v_mov_b32_e32 v107, v123
	v_mov_b32_e32 v106, v123
	v_mov_b32_e32 v105, v123
	v_mov_b32_e32 v104, v123
	v_mov_b32_e32 v99, v123
	v_mov_b32_e32 v98, v123
	v_mov_b32_e32 v97, v123
	v_mov_b32_e32 v96, v123
	v_mov_b32_e32 v91, v123
	v_mov_b32_e32 v90, v123
	v_mov_b32_e32 v89, v123
	v_mov_b32_e32 v88, v123
	v_mov_b32_e32 v83, v123
	v_mov_b32_e32 v82, v123
	v_mov_b32_e32 v81, v123
	v_mov_b32_e32 v80, v123
	v_mov_b32_e32 v75, v123
	v_mov_b32_e32 v74, v123
	v_mov_b32_e32 v73, v123
	v_mov_b32_e32 v72, v123
	v_mov_b32_e32 v67, v123
	v_mov_b32_e32 v66, v123
	v_mov_b32_e32 v65, v123
	v_mov_b32_e32 v64, v123
	v_mov_b32_e32 v63, v123
	v_mov_b32_e32 v62, v123
	v_mov_b32_e32 v61, v123
	v_mov_b32_e32 v60, v123
	v_mov_b32_e32 v55, v123
	v_mov_b32_e32 v54, v123
	v_mov_b32_e32 v53, v123
	v_mov_b32_e32 v52, v123
	v_mov_b32_e32 v47, v123
	v_mov_b32_e32 v46, v123
	v_mov_b32_e32 v45, v123
	v_mov_b32_e32 v44, v123
	v_mov_b32_e32 v39, v123
	v_mov_b32_e32 v38, v123
	v_mov_b32_e32 v37, v123
	v_mov_b32_e32 v36, v123
	v_mov_b32_e32 v31, v123
	v_mov_b32_e32 v30, v123
	v_mov_b32_e32 v29, v123
	v_mov_b32_e32 v28, v123
	v_mov_b32_e32 v23, v123
	v_mov_b32_e32 v22, v123
	v_mov_b32_e32 v21, v123
	v_mov_b32_e32 v20, v123
	v_mov_b32_e32 v15, v123
	v_mov_b32_e32 v14, v123
	v_mov_b32_e32 v13, v123
	v_mov_b32_e32 v12, v123
	v_mov_b32_e32 v7, v123
	v_mov_b32_e32 v6, v123
	v_mov_b32_e32 v5, v123
	v_mov_b32_e32 v4, v123
	v_mov_b32_e32 v59, v123
	v_mov_b32_e32 v58, v123
	v_mov_b32_e32 v57, v123
	v_mov_b32_e32 v56, v123
	v_mov_b32_e32 v51, v123
	v_mov_b32_e32 v50, v123
	v_mov_b32_e32 v49, v123
	v_mov_b32_e32 v48, v123
	v_mov_b32_e32 v43, v123
	v_mov_b32_e32 v42, v123
	v_mov_b32_e32 v41, v123
	v_mov_b32_e32 v40, v123
	v_mov_b32_e32 v35, v123
	v_mov_b32_e32 v34, v123
	v_mov_b32_e32 v33, v123
	v_mov_b32_e32 v32, v123
	v_mov_b32_e32 v27, v123
	v_mov_b32_e32 v26, v123
	v_mov_b32_e32 v25, v123
	v_mov_b32_e32 v24, v123
	v_mov_b32_e32 v19, v123
	v_mov_b32_e32 v18, v123
	v_mov_b32_e32 v17, v123
	v_mov_b32_e32 v16, v123
	v_mov_b32_e32 v11, v123
	v_mov_b32_e32 v10, v123
	v_mov_b32_e32 v9, v123
	v_mov_b32_e32 v8, v123
	v_mov_b32_e32 v3, v123
	v_mov_b32_e32 v2, v123
	v_mov_b32_e32 v1, v123
	v_mov_b32_e32 v0, v123

.LBB0_1001:
	s_and_b64 vcc, exec, s[4:5]
	s_waitcnt lgkmcnt(0)
	s_cbranch_vccnz .Lzx1003
	s_add_u32 s44, s44, 0x80
	s_addc_u32 s45, s45, 0
	s_add_u32 s59, s46, 0x100
	v_mov_b32_e32 v0, 0
	s_addc_u32 s60, s47, 0
	s_mov_b32 s46, 0
	v_mov_b32_e32 v1, v0
	v_mov_b32_e32 v2, v0
	v_mov_b32_e32 v3, v0
	v_mov_b32_e32 v4, v0
	v_mov_b32_e32 v5, v0
	v_mov_b32_e32 v6, v0
	v_mov_b32_e32 v7, v0
	v_mov_b32_e32 v16, v0
	v_mov_b32_e32 v17, v0
	v_mov_b32_e32 v18, v0
	v_mov_b32_e32 v19, v0
	v_mov_b32_e32 v20, v0
	v_mov_b32_e32 v21, v0
	v_mov_b32_e32 v22, v0
	v_mov_b32_e32 v23, v0
	v_mov_b32_e32 v32, v0
	v_mov_b32_e32 v33, v0
	v_mov_b32_e32 v34, v0
	v_mov_b32_e32 v35, v0
	v_mov_b32_e32 v36, v0
	v_mov_b32_e32 v37, v0
	v_mov_b32_e32 v38, v0
	v_mov_b32_e32 v39, v0
	v_mov_b32_e32 v48, v0
	v_mov_b32_e32 v49, v0
	v_mov_b32_e32 v50, v0
	v_mov_b32_e32 v51, v0
	v_mov_b32_e32 v52, v0
	v_mov_b32_e32 v53, v0
	v_mov_b32_e32 v54, v0
	v_mov_b32_e32 v55, v0
	v_mov_b32_e32 v8, v0
	v_mov_b32_e32 v9, v0
	v_mov_b32_e32 v10, v0
	v_mov_b32_e32 v11, v0
	v_mov_b32_e32 v12, v0
	v_mov_b32_e32 v13, v0
	v_mov_b32_e32 v14, v0
	v_mov_b32_e32 v15, v0
	v_mov_b32_e32 v24, v0
	v_mov_b32_e32 v25, v0
	v_mov_b32_e32 v26, v0
	v_mov_b32_e32 v27, v0
	v_mov_b32_e32 v28, v0
	v_mov_b32_e32 v29, v0
	v_mov_b32_e32 v30, v0
	v_mov_b32_e32 v31, v0
	v_mov_b32_e32 v40, v0
	v_mov_b32_e32 v41, v0
	v_mov_b32_e32 v42, v0
	v_mov_b32_e32 v43, v0
	v_mov_b32_e32 v44, v0
	v_mov_b32_e32 v45, v0
	v_mov_b32_e32 v46, v0
	v_mov_b32_e32 v47, v0
	v_mov_b32_e32 v56, v0
	v_mov_b32_e32 v57, v0
	v_mov_b32_e32 v58, v0
	v_mov_b32_e32 v59, v0
	v_mov_b32_e32 v60, v0
	v_mov_b32_e32 v61, v0
	v_mov_b32_e32 v62, v0
	v_mov_b32_e32 v63, v0
	v_mov_b32_e32 v64, v0
	v_mov_b32_e32 v65, v0
	v_mov_b32_e32 v66, v0
	v_mov_b32_e32 v67, v0
	v_mov_b32_e32 v68, v0
	v_mov_b32_e32 v69, v0
	v_mov_b32_e32 v70, v0
	v_mov_b32_e32 v71, v0
	v_mov_b32_e32 v80, v0
	v_mov_b32_e32 v81, v0
	v_mov_b32_e32 v82, v0
	v_mov_b32_e32 v83, v0
	v_mov_b32_e32 v84, v0
	v_mov_b32_e32 v85, v0
	v_mov_b32_e32 v86, v0
	v_mov_b32_e32 v87, v0
	v_mov_b32_e32 v96, v0
	v_mov_b32_e32 v97, v0
	v_mov_b32_e32 v98, v0
	v_mov_b32_e32 v99, v0
	v_mov_b32_e32 v100, v0
	v_mov_b32_e32 v101, v0
	v_mov_b32_e32 v102, v0
	v_mov_b32_e32 v103, v0
	v_mov_b32_e32 v112, v0
	v_mov_b32_e32 v113, v0
	v_mov_b32_e32 v114, v0
	v_mov_b32_e32 v115, v0
	v_mov_b32_e32 v116, v0
	v_mov_b32_e32 v117, v0
	v_mov_b32_e32 v118, v0
	v_mov_b32_e32 v119, v0
	v_mov_b32_e32 v72, v0
	v_mov_b32_e32 v73, v0
	v_mov_b32_e32 v74, v0
	v_mov_b32_e32 v75, v0
	v_mov_b32_e32 v76, v0
	v_mov_b32_e32 v77, v0
	v_mov_b32_e32 v78, v0
	v_mov_b32_e32 v79, v0
	v_mov_b32_e32 v88, v0
	v_mov_b32_e32 v89, v0
	v_mov_b32_e32 v90, v0
	v_mov_b32_e32 v91, v0
	v_mov_b32_e32 v92, v0
	v_mov_b32_e32 v93, v0
	v_mov_b32_e32 v94, v0
	v_mov_b32_e32 v95, v0
	v_mov_b32_e32 v104, v0
	v_mov_b32_e32 v105, v0
	v_mov_b32_e32 v106, v0
	v_mov_b32_e32 v107, v0
	v_mov_b32_e32 v108, v0
	v_mov_b32_e32 v109, v0
	v_mov_b32_e32 v110, v0
	v_mov_b32_e32 v111, v0
	v_mov_b32_e32 v120, v0
	v_mov_b32_e32 v121, v0
	v_mov_b32_e32 v122, v0
	v_mov_b32_e32 v123, v0
	v_mov_b32_e32 v124, v0
	v_mov_b32_e32 v125, v0
	v_mov_b32_e32 v126, v0
	v_mov_b32_e32 v127, v0
.LBB0_1003:
	ds_read_b128 v[144:147], v151
	ds_read_b128 v[154:157], v151 offset:1024
	ds_read_b128 v[158:161], v151 offset:2048
	ds_read_b128 v[162:165], v151 offset:3072
	ds_read_b128 v[166:169], v152
	ds_read_b128 v[170:173], v152 offset:1024
	ds_read_b128 v[174:177], v152 offset:2048
	ds_read_b128 v[178:181], v152 offset:3072
	s_add_i32 s61, s46, 2
	s_add_u32 s62, s44, 0x80
	s_addc_u32 s47, s45, 0
	s_cmp_eq_u32 s52, s46
	s_cselect_b32 s46, s8, s62
	s_cselect_b32 s47, s9, s47
	s_cselect_b32 s63, s43, s60
	s_cselect_b32 s62, s42, s59
	v_lshl_add_u64 v[182:183], s[44:45], 0, v[136:137]
	s_add_i32 m0, s3, 0xc000
	ds_read_b128 v[186:189], v153
	ds_read_b128 v[190:193], v153 offset:1024
	ds_read_b128 v[194:197], v153 offset:2048
	ds_read_b128 v[198:201], v153 offset:3072
	ds_read_b128 v[202:205], v153 offset:4096
	ds_read_b128 v[206:209], v153 offset:5120
	ds_read_b128 v[210:213], v153 offset:6144
	ds_read_b128 v[214:217], v153 offset:7168
	global_load_lds_dwordx4 v[182:183], off
	v_lshl_add_u64 v[182:183], s[44:45], 0, v[138:139]
	s_add_i32 m0, s3, 0xe000
	s_nop 0
	global_load_lds_dwordx4 v[182:183], off
	s_waitcnt vmcnt(8)
	s_waitcnt lgkmcnt(0)
	s_barrier
	s_setprio 1
	s_waitcnt lgkmcnt(0)
	v_mfma_f32_16x16x32_bf16 v[124:127], v[144:147], v[186:189], v[124:127]
	v_mfma_f32_16x16x32_bf16 v[120:123], v[158:161], v[186:189], v[120:123]
	v_mfma_f32_16x16x32_bf16 v[108:111], v[144:147], v[194:197], v[108:111]
	v_mfma_f32_16x16x32_bf16 v[104:107], v[158:161], v[194:197], v[104:107]
	v_mfma_f32_16x16x32_bf16 v[92:95], v[144:147], v[202:205], v[92:95]
	v_mfma_f32_16x16x32_bf16 v[88:91], v[158:161], v[202:205], v[88:91]
	v_mfma_f32_16x16x32_bf16 v[76:79], v[144:147], v[210:213], v[76:79]
	v_mfma_f32_16x16x32_bf16 v[72:75], v[158:161], v[210:213], v[72:75]
	v_mfma_f32_16x16x32_bf16 v[124:127], v[154:157], v[190:193], v[124:127]
	v_mfma_f32_16x16x32_bf16 v[120:123], v[162:165], v[190:193], v[120:123]
	v_mfma_f32_16x16x32_bf16 v[108:111], v[154:157], v[198:201], v[108:111]
	v_mfma_f32_16x16x32_bf16 v[104:107], v[162:165], v[198:201], v[104:107]
	v_mfma_f32_16x16x32_bf16 v[92:95], v[154:157], v[206:209], v[92:95]
	v_mfma_f32_16x16x32_bf16 v[88:91], v[162:165], v[206:209], v[88:91]
	v_mfma_f32_16x16x32_bf16 v[76:79], v[154:157], v[214:217], v[76:79]
	v_mfma_f32_16x16x32_bf16 v[72:75], v[162:165], v[214:217], v[72:75]
	s_setprio 0
	s_setprio 1
	v_mfma_f32_16x16x32_bf16 v[116:119], v[166:169], v[186:189], v[116:119]
	v_mfma_f32_16x16x32_bf16 v[112:115], v[174:177], v[186:189], v[112:115]
	v_mfma_f32_16x16x32_bf16 v[100:103], v[166:169], v[194:197], v[100:103]
	v_mfma_f32_16x16x32_bf16 v[96:99], v[174:177], v[194:197], v[96:99]
	v_mfma_f32_16x16x32_bf16 v[84:87], v[166:169], v[202:205], v[84:87]
	v_mfma_f32_16x16x32_bf16 v[80:83], v[174:177], v[202:205], v[80:83]
	v_mfma_f32_16x16x32_bf16 v[68:71], v[166:169], v[210:213], v[68:71]
	v_mfma_f32_16x16x32_bf16 v[64:67], v[174:177], v[210:213], v[64:67]
	v_mfma_f32_16x16x32_bf16 v[116:119], v[170:173], v[190:193], v[116:119]
	v_mfma_f32_16x16x32_bf16 v[112:115], v[178:181], v[190:193], v[112:115]
	v_mfma_f32_16x16x32_bf16 v[100:103], v[170:173], v[198:201], v[100:103]
	v_mfma_f32_16x16x32_bf16 v[96:99], v[178:181], v[198:201], v[96:99]
	v_mfma_f32_16x16x32_bf16 v[84:87], v[170:173], v[206:209], v[84:87]
	v_mfma_f32_16x16x32_bf16 v[80:83], v[178:181], v[206:209], v[80:83]
	v_mfma_f32_16x16x32_bf16 v[68:71], v[170:173], v[214:217], v[68:71]
	v_mfma_f32_16x16x32_bf16 v[64:67], v[178:181], v[214:217], v[64:67]
	s_setprio 0
	s_barrier
	s_add_i32 s64, s53, s31
	v_lshl_add_u64 v[182:183], s[62:63], 0, v[130:131]
	s_mov_b32 m0, s64
	ds_read_b128 v[186:189], v153 offset:16384
	ds_read_b128 v[190:193], v153 offset:17408
	ds_read_b128 v[194:197], v153 offset:18432
	ds_read_b128 v[198:201], v153 offset:19456
	ds_read_b128 v[202:205], v153 offset:20480
	ds_read_b128 v[206:209], v153 offset:21504
	ds_read_b128 v[210:213], v153 offset:22528
	ds_read_b128 v[214:217], v153 offset:23552
	global_load_lds_dwordx4 v[182:183], off
	s_add_i32 m0, s64, 0x2000
	v_lshl_add_u64 v[224:225], s[62:63], 0, v[134:135]
	s_add_u32 s62, s62, s16
	s_addc_u32 s63, s63, s17
	s_add_i32 s64, s54, s31
	global_load_lds_dwordx4 v[224:225], off
	v_lshl_add_u64 v[226:227], s[62:63], 0, v[130:131]
	s_mov_b32 m0, s64
	v_lshl_add_u64 v[228:229], s[62:63], 0, v[134:135]
	global_load_lds_dwordx4 v[226:227], off
	s_add_i32 m0, s64, 0x2000
	v_lshl_add_u64 v[230:231], s[46:47], 0, v[128:129]
	global_load_lds_dwordx4 v[228:229], off
	s_mov_b32 m0, s3
	v_lshl_add_u64 v[232:233], s[46:47], 0, v[132:133]
	global_load_lds_dwordx4 v[230:231], off
	s_mov_b32 m0, s28
	s_nop 0
	global_load_lds_dwordx4 v[232:233], off
	s_waitcnt vmcnt(8)
	s_waitcnt lgkmcnt(0)
	s_barrier
	s_setprio 1
	s_waitcnt lgkmcnt(0)
	v_mfma_f32_16x16x32_bf16 v[60:63], v[144:147], v[186:189], v[60:63]
	v_mfma_f32_16x16x32_bf16 v[56:59], v[158:161], v[186:189], v[56:59]
	v_mfma_f32_16x16x32_bf16 v[44:47], v[144:147], v[194:197], v[44:47]
	v_mfma_f32_16x16x32_bf16 v[40:43], v[158:161], v[194:197], v[40:43]
	v_mfma_f32_16x16x32_bf16 v[28:31], v[144:147], v[202:205], v[28:31]
	v_mfma_f32_16x16x32_bf16 v[24:27], v[158:161], v[202:205], v[24:27]
	v_mfma_f32_16x16x32_bf16 v[12:15], v[144:147], v[210:213], v[12:15]
	v_mfma_f32_16x16x32_bf16 v[8:11], v[158:161], v[210:213], v[8:11]
	v_mfma_f32_16x16x32_bf16 v[60:63], v[154:157], v[190:193], v[60:63]
	v_mfma_f32_16x16x32_bf16 v[56:59], v[162:165], v[190:193], v[56:59]
	v_mfma_f32_16x16x32_bf16 v[44:47], v[154:157], v[198:201], v[44:47]
	v_mfma_f32_16x16x32_bf16 v[40:43], v[162:165], v[198:201], v[40:43]
	v_mfma_f32_16x16x32_bf16 v[28:31], v[154:157], v[206:209], v[28:31]
	v_mfma_f32_16x16x32_bf16 v[24:27], v[162:165], v[206:209], v[24:27]
	v_mfma_f32_16x16x32_bf16 v[12:15], v[154:157], v[214:217], v[12:15]
	v_mfma_f32_16x16x32_bf16 v[8:11], v[162:165], v[214:217], v[8:11]
	s_setprio 0
	s_setprio 1
	v_mfma_f32_16x16x32_bf16 v[52:55], v[166:169], v[186:189], v[52:55]
	v_mfma_f32_16x16x32_bf16 v[48:51], v[174:177], v[186:189], v[48:51]
	v_mfma_f32_16x16x32_bf16 v[36:39], v[166:169], v[194:197], v[36:39]
	v_mfma_f32_16x16x32_bf16 v[32:35], v[174:177], v[194:197], v[32:35]
	v_mfma_f32_16x16x32_bf16 v[20:23], v[166:169], v[202:205], v[20:23]
	v_mfma_f32_16x16x32_bf16 v[16:19], v[174:177], v[202:205], v[16:19]
	v_mfma_f32_16x16x32_bf16 v[4:7], v[166:169], v[210:213], v[4:7]
	v_mfma_f32_16x16x32_bf16 v[0:3], v[174:177], v[210:213], v[0:3]
	v_mfma_f32_16x16x32_bf16 v[52:55], v[170:173], v[190:193], v[52:55]
	v_mfma_f32_16x16x32_bf16 v[48:51], v[178:181], v[190:193], v[48:51]
	v_mfma_f32_16x16x32_bf16 v[36:39], v[170:173], v[198:201], v[36:39]
	v_mfma_f32_16x16x32_bf16 v[32:35], v[178:181], v[198:201], v[32:35]
	v_mfma_f32_16x16x32_bf16 v[20:23], v[170:173], v[206:209], v[20:23]
	v_mfma_f32_16x16x32_bf16 v[16:19], v[178:181], v[206:209], v[16:19]
	v_mfma_f32_16x16x32_bf16 v[4:7], v[170:173], v[214:217], v[4:7]
	v_mfma_f32_16x16x32_bf16 v[0:3], v[178:181], v[214:217], v[0:3]
	s_setprio 0
	s_barrier
	s_add_i32 s62, 0, 0x18000
	s_add_i32 s63, 0, 0x1c000
	v_add_u32_e32 v162, s62, v149
	v_add_u32_e32 v178, s63, v149
	ds_read_b128 v[144:147], v162
	ds_read_b128 v[154:157], v162 offset:1024
	ds_read_b128 v[158:161], v162 offset:2048
	ds_read_b128 v[162:165], v162 offset:3072
	ds_read_b128 v[166:169], v178
	ds_read_b128 v[170:173], v178 offset:1024
	ds_read_b128 v[174:177], v178 offset:2048
	ds_read_b128 v[178:181], v178 offset:3072
	s_add_u32 s46, s46, s16
	s_addc_u32 s47, s47, s17
	s_mov_b32 m0, s33
	v_lshl_add_u64 v[234:235], s[46:47], 0, v[128:129]
	ds_read_b128 v[186:189], v153 offset:32768
	ds_read_b128 v[190:193], v153 offset:33792
	ds_read_b128 v[194:197], v153 offset:34816
	ds_read_b128 v[198:201], v153 offset:35840
	ds_read_b128 v[202:205], v153 offset:36864
	ds_read_b128 v[206:209], v153 offset:37888
	ds_read_b128 v[210:213], v153 offset:38912
	ds_read_b128 v[214:217], v153 offset:39936
	global_load_lds_dwordx4 v[234:235], off
	v_lshl_add_u64 v[234:235], s[46:47], 0, v[132:133]
	s_mov_b32 m0, s48
	s_nop 0
	global_load_lds_dwordx4 v[234:235], off
	s_waitcnt vmcnt(8)
	s_waitcnt lgkmcnt(0)
	s_barrier
	s_setprio 1
	s_waitcnt lgkmcnt(0)
	v_mfma_f32_16x16x32_bf16 v[124:127], v[144:147], v[186:189], v[124:127]
	v_mfma_f32_16x16x32_bf16 v[120:123], v[158:161], v[186:189], v[120:123]
	v_mfma_f32_16x16x32_bf16 v[108:111], v[144:147], v[194:197], v[108:111]
	v_mfma_f32_16x16x32_bf16 v[104:107], v[158:161], v[194:197], v[104:107]
	v_mfma_f32_16x16x32_bf16 v[92:95], v[144:147], v[202:205], v[92:95]
	v_mfma_f32_16x16x32_bf16 v[88:91], v[158:161], v[202:205], v[88:91]
	v_mfma_f32_16x16x32_bf16 v[76:79], v[144:147], v[210:213], v[76:79]
	v_mfma_f32_16x16x32_bf16 v[72:75], v[158:161], v[210:213], v[72:75]
	v_mfma_f32_16x16x32_bf16 v[124:127], v[154:157], v[190:193], v[124:127]
	v_mfma_f32_16x16x32_bf16 v[120:123], v[162:165], v[190:193], v[120:123]
	v_mfma_f32_16x16x32_bf16 v[108:111], v[154:157], v[198:201], v[108:111]
	v_mfma_f32_16x16x32_bf16 v[104:107], v[162:165], v[198:201], v[104:107]
	v_mfma_f32_16x16x32_bf16 v[92:95], v[154:157], v[206:209], v[92:95]
	v_mfma_f32_16x16x32_bf16 v[88:91], v[162:165], v[206:209], v[88:91]
	v_mfma_f32_16x16x32_bf16 v[76:79], v[154:157], v[214:217], v[76:79]
	v_mfma_f32_16x16x32_bf16 v[72:75], v[162:165], v[214:217], v[72:75]
	s_setprio 0
	s_setprio 1
	v_mfma_f32_16x16x32_bf16 v[116:119], v[166:169], v[186:189], v[116:119]
	v_mfma_f32_16x16x32_bf16 v[112:115], v[174:177], v[186:189], v[112:115]
	v_mfma_f32_16x16x32_bf16 v[100:103], v[166:169], v[194:197], v[100:103]
	v_mfma_f32_16x16x32_bf16 v[96:99], v[174:177], v[194:197], v[96:99]
	v_mfma_f32_16x16x32_bf16 v[84:87], v[166:169], v[202:205], v[84:87]
	v_mfma_f32_16x16x32_bf16 v[80:83], v[174:177], v[202:205], v[80:83]
	v_mfma_f32_16x16x32_bf16 v[68:71], v[166:169], v[210:213], v[68:71]
	v_mfma_f32_16x16x32_bf16 v[64:67], v[174:177], v[210:213], v[64:67]
	v_mfma_f32_16x16x32_bf16 v[116:119], v[170:173], v[190:193], v[116:119]
	v_mfma_f32_16x16x32_bf16 v[112:115], v[178:181], v[190:193], v[112:115]
	v_mfma_f32_16x16x32_bf16 v[100:103], v[170:173], v[198:201], v[100:103]
	v_mfma_f32_16x16x32_bf16 v[96:99], v[178:181], v[198:201], v[96:99]
	v_mfma_f32_16x16x32_bf16 v[84:87], v[170:173], v[206:209], v[84:87]
	v_mfma_f32_16x16x32_bf16 v[80:83], v[178:181], v[206:209], v[80:83]
	v_mfma_f32_16x16x32_bf16 v[68:71], v[170:173], v[214:217], v[68:71]
	v_mfma_f32_16x16x32_bf16 v[64:67], v[178:181], v[214:217], v[64:67]
	s_setprio 0
	s_barrier
	s_add_i32 s46, s62, s31
	v_lshl_add_u64 v[182:183], v[182:183], 0, s[40:41]
	s_mov_b32 m0, s46
	ds_read_b128 v[186:189], v153 offset:49152
	ds_read_b128 v[190:193], v153 offset:50176
	ds_read_b128 v[194:197], v153 offset:51200
	ds_read_b128 v[198:201], v153 offset:52224
	ds_read_b128 v[202:205], v153 offset:53248
	ds_read_b128 v[206:209], v153 offset:54272
	ds_read_b128 v[210:213], v153 offset:55296
	ds_read_b128 v[214:217], v153 offset:56320
	global_load_lds_dwordx4 v[182:183], off
	v_lshl_add_u64 v[182:183], v[224:225], 0, s[40:41]
	s_add_i32 m0, s46, 0x2000
	s_add_i32 s46, s63, s31
	global_load_lds_dwordx4 v[182:183], off
	v_lshl_add_u64 v[182:183], v[226:227], 0, s[40:41]
	s_mov_b32 m0, s46
	s_nop 0
	global_load_lds_dwordx4 v[182:183], off
	v_lshl_add_u64 v[182:183], v[228:229], 0, s[40:41]
	s_add_i32 m0, s46, 0x2000
	s_nop 0
	global_load_lds_dwordx4 v[182:183], off
	v_lshl_add_u64 v[182:183], v[230:231], 0, s[40:41]
	s_mov_b32 m0, s49
	s_nop 0
	global_load_lds_dwordx4 v[182:183], off
	v_lshl_add_u64 v[182:183], v[232:233], 0, s[40:41]
	s_mov_b32 m0, s50
	s_nop 0
	global_load_lds_dwordx4 v[182:183], off
	s_waitcnt vmcnt(8)
	s_waitcnt lgkmcnt(0)
	s_barrier
	s_setprio 1
	s_waitcnt lgkmcnt(0)
	v_mfma_f32_16x16x32_bf16 v[60:63], v[144:147], v[186:189], v[60:63]
	v_mfma_f32_16x16x32_bf16 v[56:59], v[158:161], v[186:189], v[56:59]
	v_mfma_f32_16x16x32_bf16 v[44:47], v[144:147], v[194:197], v[44:47]
	v_mfma_f32_16x16x32_bf16 v[40:43], v[158:161], v[194:197], v[40:43]
	v_mfma_f32_16x16x32_bf16 v[28:31], v[144:147], v[202:205], v[28:31]
	v_mfma_f32_16x16x32_bf16 v[24:27], v[158:161], v[202:205], v[24:27]
	v_mfma_f32_16x16x32_bf16 v[12:15], v[144:147], v[210:213], v[12:15]
	v_mfma_f32_16x16x32_bf16 v[8:11], v[158:161], v[210:213], v[8:11]
	v_mfma_f32_16x16x32_bf16 v[60:63], v[154:157], v[190:193], v[60:63]
	v_mfma_f32_16x16x32_bf16 v[56:59], v[162:165], v[190:193], v[56:59]
	v_mfma_f32_16x16x32_bf16 v[44:47], v[154:157], v[198:201], v[44:47]
	v_mfma_f32_16x16x32_bf16 v[40:43], v[162:165], v[198:201], v[40:43]
	v_mfma_f32_16x16x32_bf16 v[28:31], v[154:157], v[206:209], v[28:31]
	v_mfma_f32_16x16x32_bf16 v[24:27], v[162:165], v[206:209], v[24:27]
	v_mfma_f32_16x16x32_bf16 v[12:15], v[154:157], v[214:217], v[12:15]
	v_mfma_f32_16x16x32_bf16 v[8:11], v[162:165], v[214:217], v[8:11]
	s_setprio 0
	s_setprio 1
	v_mfma_f32_16x16x32_bf16 v[52:55], v[166:169], v[186:189], v[52:55]
	v_mfma_f32_16x16x32_bf16 v[48:51], v[174:177], v[186:189], v[48:51]
	v_mfma_f32_16x16x32_bf16 v[36:39], v[166:169], v[194:197], v[36:39]
	v_mfma_f32_16x16x32_bf16 v[32:35], v[174:177], v[194:197], v[32:35]
	v_mfma_f32_16x16x32_bf16 v[20:23], v[166:169], v[202:205], v[20:23]
	v_mfma_f32_16x16x32_bf16 v[16:19], v[174:177], v[202:205], v[16:19]
	v_mfma_f32_16x16x32_bf16 v[4:7], v[166:169], v[210:213], v[4:7]
	v_mfma_f32_16x16x32_bf16 v[0:3], v[174:177], v[210:213], v[0:3]
	v_mfma_f32_16x16x32_bf16 v[52:55], v[170:173], v[190:193], v[52:55]
	v_mfma_f32_16x16x32_bf16 v[48:51], v[178:181], v[190:193], v[48:51]
	v_mfma_f32_16x16x32_bf16 v[36:39], v[170:173], v[198:201], v[36:39]
	v_mfma_f32_16x16x32_bf16 v[32:35], v[178:181], v[198:201], v[32:35]
	v_mfma_f32_16x16x32_bf16 v[20:23], v[170:173], v[206:209], v[20:23]
	v_mfma_f32_16x16x32_bf16 v[16:19], v[178:181], v[206:209], v[16:19]
	v_mfma_f32_16x16x32_bf16 v[4:7], v[170:173], v[214:217], v[4:7]
	v_mfma_f32_16x16x32_bf16 v[0:3], v[178:181], v[214:217], v[0:3]
	s_setprio 0
	s_barrier
	s_add_u32 s44, s44, 0x100
	s_addc_u32 s45, s45, 0
	s_add_u32 s59, s59, 0x100
	s_addc_u32 s60, s60, 0
	s_cmp_ge_i32 s61, s51
	s_mov_b32 s46, s61
	s_cbranch_scc0 .LBB0_1003
	s_branch .LBB0_1004

.LBB0_1110:
	s_andn2_b64 vcc, exec, s[38:39]
	s_cbranch_vccnz .Lzx1112
	s_add_u32 s4, s48, 0x80
	s_addc_u32 s5, s49, 0
	s_add_u32 s33, s46, 0x100
	v_mov_b32_e32 v0, 0
	s_addc_u32 s48, s47, 0
	s_mov_b32 s46, 0
	v_mov_b32_e32 v1, v0
	v_mov_b32_e32 v2, v0
	v_mov_b32_e32 v3, v0
	v_mov_b32_e32 v4, v0
	v_mov_b32_e32 v5, v0
	v_mov_b32_e32 v6, v0
	v_mov_b32_e32 v7, v0
	v_mov_b32_e32 v16, v0
	v_mov_b32_e32 v17, v0
	v_mov_b32_e32 v18, v0
	v_mov_b32_e32 v19, v0
	v_mov_b32_e32 v20, v0
	v_mov_b32_e32 v21, v0
	v_mov_b32_e32 v22, v0
	v_mov_b32_e32 v23, v0
	v_mov_b32_e32 v32, v0
	v_mov_b32_e32 v33, v0
	v_mov_b32_e32 v34, v0
	v_mov_b32_e32 v35, v0
	v_mov_b32_e32 v36, v0
	v_mov_b32_e32 v37, v0
	v_mov_b32_e32 v38, v0
	v_mov_b32_e32 v39, v0
	v_mov_b32_e32 v48, v0
	v_mov_b32_e32 v49, v0
	v_mov_b32_e32 v50, v0
	v_mov_b32_e32 v51, v0
	v_mov_b32_e32 v52, v0
	v_mov_b32_e32 v53, v0
	v_mov_b32_e32 v54, v0
	v_mov_b32_e32 v55, v0
	v_mov_b32_e32 v8, v0
	v_mov_b32_e32 v9, v0
	v_mov_b32_e32 v10, v0
	v_mov_b32_e32 v11, v0
	v_mov_b32_e32 v12, v0
	v_mov_b32_e32 v13, v0
	v_mov_b32_e32 v14, v0
	v_mov_b32_e32 v15, v0
	v_mov_b32_e32 v24, v0
	v_mov_b32_e32 v25, v0
	v_mov_b32_e32 v26, v0
	v_mov_b32_e32 v27, v0
	v_mov_b32_e32 v28, v0
	v_mov_b32_e32 v29, v0
	v_mov_b32_e32 v30, v0
	v_mov_b32_e32 v31, v0
	v_mov_b32_e32 v40, v0
	v_mov_b32_e32 v41, v0
	v_mov_b32_e32 v42, v0
	v_mov_b32_e32 v43, v0
	v_mov_b32_e32 v44, v0
	v_mov_b32_e32 v45, v0
	v_mov_b32_e32 v46, v0
	v_mov_b32_e32 v47, v0
	v_mov_b32_e32 v56, v0
	v_mov_b32_e32 v57, v0
	v_mov_b32_e32 v58, v0
	v_mov_b32_e32 v59, v0
	v_mov_b32_e32 v60, v0
	v_mov_b32_e32 v61, v0
	v_mov_b32_e32 v62, v0
	v_mov_b32_e32 v63, v0
	v_mov_b32_e32 v64, v0
	v_mov_b32_e32 v65, v0
	v_mov_b32_e32 v66, v0
	v_mov_b32_e32 v67, v0
	v_mov_b32_e32 v68, v0
	v_mov_b32_e32 v69, v0
	v_mov_b32_e32 v70, v0
	v_mov_b32_e32 v71, v0
	v_mov_b32_e32 v80, v0
	v_mov_b32_e32 v81, v0
	v_mov_b32_e32 v82, v0
	v_mov_b32_e32 v83, v0
	v_mov_b32_e32 v84, v0
	v_mov_b32_e32 v85, v0
	v_mov_b32_e32 v86, v0
	v_mov_b32_e32 v87, v0
	v_mov_b32_e32 v96, v0
	v_mov_b32_e32 v97, v0
	v_mov_b32_e32 v98, v0
	v_mov_b32_e32 v99, v0
	v_mov_b32_e32 v100, v0
	v_mov_b32_e32 v101, v0
	v_mov_b32_e32 v102, v0
	v_mov_b32_e32 v103, v0
	v_mov_b32_e32 v112, v0
	v_mov_b32_e32 v113, v0
	v_mov_b32_e32 v114, v0
	v_mov_b32_e32 v115, v0
	v_mov_b32_e32 v116, v0
	v_mov_b32_e32 v117, v0
	v_mov_b32_e32 v118, v0
	v_mov_b32_e32 v119, v0
	v_mov_b32_e32 v72, v0
	v_mov_b32_e32 v73, v0
	v_mov_b32_e32 v74, v0
	v_mov_b32_e32 v75, v0
	v_mov_b32_e32 v76, v0
	v_mov_b32_e32 v77, v0
	v_mov_b32_e32 v78, v0
	v_mov_b32_e32 v79, v0
	v_mov_b32_e32 v88, v0
	v_mov_b32_e32 v89, v0
	v_mov_b32_e32 v90, v0
	v_mov_b32_e32 v91, v0
	v_mov_b32_e32 v92, v0
	v_mov_b32_e32 v93, v0
	v_mov_b32_e32 v94, v0
	v_mov_b32_e32 v95, v0
	v_mov_b32_e32 v104, v0
	v_mov_b32_e32 v105, v0
	v_mov_b32_e32 v106, v0
	v_mov_b32_e32 v107, v0
	v_mov_b32_e32 v108, v0
	v_mov_b32_e32 v109, v0
	v_mov_b32_e32 v110, v0
	v_mov_b32_e32 v111, v0
	v_mov_b32_e32 v120, v0
	v_mov_b32_e32 v121, v0
	v_mov_b32_e32 v122, v0
	v_mov_b32_e32 v123, v0
	v_mov_b32_e32 v124, v0
	v_mov_b32_e32 v125, v0
	v_mov_b32_e32 v126, v0
	v_mov_b32_e32 v127, v0
.LBB0_1112:
	ds_read_b128 v[144:147], v151
	ds_read_b128 v[156:159], v151 offset:1024
	ds_read_b128 v[160:163], v151 offset:2048
	ds_read_b128 v[164:167], v151 offset:3072
	ds_read_b128 v[168:171], v152
	ds_read_b128 v[172:175], v152 offset:1024
	ds_read_b128 v[176:179], v152 offset:2048
	ds_read_b128 v[180:183], v152 offset:3072
	s_add_i32 s49, s46, 2
	s_add_u32 s52, s4, 0x80
	s_addc_u32 s47, s5, 0
	s_cmp_eq_u32 s60, s46
	s_cselect_b32 s46, s42, s52
	s_cselect_b32 s47, s43, s47
	s_cselect_b32 s53, s45, s48
	s_cselect_b32 s52, s44, s33
	v_lshl_add_u64 v[224:225], s[4:5], 0, v[136:137]
	s_add_i32 m0, s50, 0xc000
	ds_read_b128 v[186:189], v153
	ds_read_b128 v[190:193], v153 offset:1024
	ds_read_b128 v[194:197], v153 offset:2048
	ds_read_b128 v[198:201], v153 offset:3072
	ds_read_b128 v[202:205], v153 offset:4096
	ds_read_b128 v[206:209], v153 offset:5120
	ds_read_b128 v[210:213], v153 offset:6144
	ds_read_b128 v[214:217], v153 offset:7168
	global_load_lds_dwordx4 v[224:225], off
	v_lshl_add_u64 v[224:225], s[4:5], 0, v[138:139]
	s_add_i32 m0, s50, 0xe000
	s_nop 0
	global_load_lds_dwordx4 v[224:225], off
	s_waitcnt vmcnt(8)
	s_waitcnt lgkmcnt(0)
	s_barrier
	s_setprio 1
	s_waitcnt lgkmcnt(0)
	v_mfma_f32_16x16x32_bf16 v[124:127], v[144:147], v[186:189], v[124:127]
	v_mfma_f32_16x16x32_bf16 v[120:123], v[160:163], v[186:189], v[120:123]
	v_mfma_f32_16x16x32_bf16 v[108:111], v[144:147], v[194:197], v[108:111]
	v_mfma_f32_16x16x32_bf16 v[104:107], v[160:163], v[194:197], v[104:107]
	v_mfma_f32_16x16x32_bf16 v[92:95], v[144:147], v[202:205], v[92:95]
	v_mfma_f32_16x16x32_bf16 v[88:91], v[160:163], v[202:205], v[88:91]
	v_mfma_f32_16x16x32_bf16 v[76:79], v[144:147], v[210:213], v[76:79]
	v_mfma_f32_16x16x32_bf16 v[72:75], v[160:163], v[210:213], v[72:75]
	v_mfma_f32_16x16x32_bf16 v[124:127], v[156:159], v[190:193], v[124:127]
	v_mfma_f32_16x16x32_bf16 v[120:123], v[164:167], v[190:193], v[120:123]
	v_mfma_f32_16x16x32_bf16 v[108:111], v[156:159], v[198:201], v[108:111]
	v_mfma_f32_16x16x32_bf16 v[104:107], v[164:167], v[198:201], v[104:107]
	v_mfma_f32_16x16x32_bf16 v[92:95], v[156:159], v[206:209], v[92:95]
	v_mfma_f32_16x16x32_bf16 v[88:91], v[164:167], v[206:209], v[88:91]
	v_mfma_f32_16x16x32_bf16 v[76:79], v[156:159], v[214:217], v[76:79]
	v_mfma_f32_16x16x32_bf16 v[72:75], v[164:167], v[214:217], v[72:75]
	s_setprio 0
	s_setprio 1
	v_mfma_f32_16x16x32_bf16 v[116:119], v[168:171], v[186:189], v[116:119]
	v_mfma_f32_16x16x32_bf16 v[112:115], v[176:179], v[186:189], v[112:115]
	v_mfma_f32_16x16x32_bf16 v[100:103], v[168:171], v[194:197], v[100:103]
	v_mfma_f32_16x16x32_bf16 v[96:99], v[176:179], v[194:197], v[96:99]
	v_mfma_f32_16x16x32_bf16 v[84:87], v[168:171], v[202:205], v[84:87]
	v_mfma_f32_16x16x32_bf16 v[80:83], v[176:179], v[202:205], v[80:83]
	v_mfma_f32_16x16x32_bf16 v[68:71], v[168:171], v[210:213], v[68:71]
	v_mfma_f32_16x16x32_bf16 v[64:67], v[176:179], v[210:213], v[64:67]
	v_mfma_f32_16x16x32_bf16 v[116:119], v[172:175], v[190:193], v[116:119]
	v_mfma_f32_16x16x32_bf16 v[112:115], v[180:183], v[190:193], v[112:115]
	v_mfma_f32_16x16x32_bf16 v[100:103], v[172:175], v[198:201], v[100:103]
	v_mfma_f32_16x16x32_bf16 v[96:99], v[180:183], v[198:201], v[96:99]
	v_mfma_f32_16x16x32_bf16 v[84:87], v[172:175], v[206:209], v[84:87]
	v_mfma_f32_16x16x32_bf16 v[80:83], v[180:183], v[206:209], v[80:83]
	v_mfma_f32_16x16x32_bf16 v[68:71], v[172:175], v[214:217], v[68:71]
	v_mfma_f32_16x16x32_bf16 v[64:67], v[180:183], v[214:217], v[64:67]
	s_setprio 0
	s_barrier
	s_add_i32 s65, s61, s31
	v_lshl_add_u64 v[224:225], s[52:53], 0, v[130:131]
	s_mov_b32 m0, s65
	ds_read_b128 v[186:189], v153 offset:16384
	ds_read_b128 v[190:193], v153 offset:17408
	ds_read_b128 v[194:197], v153 offset:18432
	ds_read_b128 v[198:201], v153 offset:19456
	ds_read_b128 v[202:205], v153 offset:20480
	ds_read_b128 v[206:209], v153 offset:21504
	ds_read_b128 v[210:213], v153 offset:22528
	ds_read_b128 v[214:217], v153 offset:23552
	global_load_lds_dwordx4 v[224:225], off
	s_add_i32 m0, s65, 0x2000
	v_lshl_add_u64 v[226:227], s[52:53], 0, v[134:135]
	s_add_u32 s52, s52, s14
	s_addc_u32 s53, s53, s15
	s_add_i32 s65, s62, s31
	global_load_lds_dwordx4 v[226:227], off
	v_lshl_add_u64 v[228:229], s[52:53], 0, v[130:131]
	s_mov_b32 m0, s65
	v_lshl_add_u64 v[230:231], s[52:53], 0, v[134:135]
	global_load_lds_dwordx4 v[228:229], off
	s_add_i32 m0, s65, 0x2000
	v_lshl_add_u64 v[232:233], s[46:47], 0, v[128:129]
	global_load_lds_dwordx4 v[230:231], off
	s_mov_b32 m0, s50
	v_lshl_add_u64 v[234:235], s[46:47], 0, v[132:133]
	global_load_lds_dwordx4 v[232:233], off
	s_mov_b32 m0, s51
	s_nop 0
	global_load_lds_dwordx4 v[234:235], off
	s_waitcnt vmcnt(8)
	s_waitcnt lgkmcnt(0)
	s_barrier
	s_setprio 1
	s_waitcnt lgkmcnt(0)
	v_mfma_f32_16x16x32_bf16 v[60:63], v[144:147], v[186:189], v[60:63]
	v_mfma_f32_16x16x32_bf16 v[56:59], v[160:163], v[186:189], v[56:59]
	v_mfma_f32_16x16x32_bf16 v[44:47], v[144:147], v[194:197], v[44:47]
	v_mfma_f32_16x16x32_bf16 v[40:43], v[160:163], v[194:197], v[40:43]
	v_mfma_f32_16x16x32_bf16 v[28:31], v[144:147], v[202:205], v[28:31]
	v_mfma_f32_16x16x32_bf16 v[24:27], v[160:163], v[202:205], v[24:27]
	v_mfma_f32_16x16x32_bf16 v[12:15], v[144:147], v[210:213], v[12:15]
	v_mfma_f32_16x16x32_bf16 v[8:11], v[160:163], v[210:213], v[8:11]
	v_mfma_f32_16x16x32_bf16 v[60:63], v[156:159], v[190:193], v[60:63]
	v_mfma_f32_16x16x32_bf16 v[56:59], v[164:167], v[190:193], v[56:59]
	v_mfma_f32_16x16x32_bf16 v[44:47], v[156:159], v[198:201], v[44:47]
	v_mfma_f32_16x16x32_bf16 v[40:43], v[164:167], v[198:201], v[40:43]
	v_mfma_f32_16x16x32_bf16 v[28:31], v[156:159], v[206:209], v[28:31]
	v_mfma_f32_16x16x32_bf16 v[24:27], v[164:167], v[206:209], v[24:27]
	v_mfma_f32_16x16x32_bf16 v[12:15], v[156:159], v[214:217], v[12:15]
	v_mfma_f32_16x16x32_bf16 v[8:11], v[164:167], v[214:217], v[8:11]
	s_setprio 0
	s_setprio 1
	v_mfma_f32_16x16x32_bf16 v[52:55], v[168:171], v[186:189], v[52:55]
	v_mfma_f32_16x16x32_bf16 v[48:51], v[176:179], v[186:189], v[48:51]
	v_mfma_f32_16x16x32_bf16 v[36:39], v[168:171], v[194:197], v[36:39]
	v_mfma_f32_16x16x32_bf16 v[32:35], v[176:179], v[194:197], v[32:35]
	v_mfma_f32_16x16x32_bf16 v[20:23], v[168:171], v[202:205], v[20:23]
	v_mfma_f32_16x16x32_bf16 v[16:19], v[176:179], v[202:205], v[16:19]
	v_mfma_f32_16x16x32_bf16 v[4:7], v[168:171], v[210:213], v[4:7]
	v_mfma_f32_16x16x32_bf16 v[0:3], v[176:179], v[210:213], v[0:3]
	v_mfma_f32_16x16x32_bf16 v[52:55], v[172:175], v[190:193], v[52:55]
	v_mfma_f32_16x16x32_bf16 v[48:51], v[180:183], v[190:193], v[48:51]
	v_mfma_f32_16x16x32_bf16 v[36:39], v[172:175], v[198:201], v[36:39]
	v_mfma_f32_16x16x32_bf16 v[32:35], v[180:183], v[198:201], v[32:35]
	v_mfma_f32_16x16x32_bf16 v[20:23], v[172:175], v[206:209], v[20:23]
	v_mfma_f32_16x16x32_bf16 v[16:19], v[180:183], v[206:209], v[16:19]
	v_mfma_f32_16x16x32_bf16 v[4:7], v[172:175], v[214:217], v[4:7]
	v_mfma_f32_16x16x32_bf16 v[0:3], v[180:183], v[214:217], v[0:3]
	s_setprio 0
	s_barrier
	s_add_i32 s52, 0, 0x18000
	v_add_u32_e32 v155, s52, v149
	s_add_i32 s53, 0, 0x1c000
	ds_read_b128 v[144:147], v155
	ds_read_b128 v[156:159], v155 offset:1024
	ds_read_b128 v[160:163], v155 offset:2048
	ds_read_b128 v[164:167], v155 offset:3072
	v_add_u32_e32 v155, s53, v149
	ds_read_b128 v[168:171], v155
	ds_read_b128 v[172:175], v155 offset:1024
	ds_read_b128 v[176:179], v155 offset:2048
	ds_read_b128 v[180:183], v155 offset:3072
	s_add_u32 s46, s46, s14
	s_addc_u32 s47, s47, s15
	s_mov_b32 m0, s54
	v_lshl_add_u64 v[236:237], s[46:47], 0, v[128:129]
	ds_read_b128 v[186:189], v153 offset:32768
	ds_read_b128 v[190:193], v153 offset:33792
	ds_read_b128 v[194:197], v153 offset:34816
	ds_read_b128 v[198:201], v153 offset:35840
	ds_read_b128 v[202:205], v153 offset:36864
	ds_read_b128 v[206:209], v153 offset:37888
	ds_read_b128 v[210:213], v153 offset:38912
	ds_read_b128 v[214:217], v153 offset:39936
	global_load_lds_dwordx4 v[236:237], off
	v_lshl_add_u64 v[236:237], s[46:47], 0, v[132:133]
	s_mov_b32 m0, s55
	s_nop 0
	global_load_lds_dwordx4 v[236:237], off
	s_waitcnt vmcnt(8)
	s_waitcnt lgkmcnt(0)
	s_barrier
	s_setprio 1
	s_waitcnt lgkmcnt(0)
	v_mfma_f32_16x16x32_bf16 v[124:127], v[144:147], v[186:189], v[124:127]
	v_mfma_f32_16x16x32_bf16 v[120:123], v[160:163], v[186:189], v[120:123]
	v_mfma_f32_16x16x32_bf16 v[108:111], v[144:147], v[194:197], v[108:111]
	v_mfma_f32_16x16x32_bf16 v[104:107], v[160:163], v[194:197], v[104:107]
	v_mfma_f32_16x16x32_bf16 v[92:95], v[144:147], v[202:205], v[92:95]
	v_mfma_f32_16x16x32_bf16 v[88:91], v[160:163], v[202:205], v[88:91]
	v_mfma_f32_16x16x32_bf16 v[76:79], v[144:147], v[210:213], v[76:79]
	v_mfma_f32_16x16x32_bf16 v[72:75], v[160:163], v[210:213], v[72:75]
	v_mfma_f32_16x16x32_bf16 v[124:127], v[156:159], v[190:193], v[124:127]
	v_mfma_f32_16x16x32_bf16 v[120:123], v[164:167], v[190:193], v[120:123]
	v_mfma_f32_16x16x32_bf16 v[108:111], v[156:159], v[198:201], v[108:111]
	v_mfma_f32_16x16x32_bf16 v[104:107], v[164:167], v[198:201], v[104:107]
	v_mfma_f32_16x16x32_bf16 v[92:95], v[156:159], v[206:209], v[92:95]
	v_mfma_f32_16x16x32_bf16 v[88:91], v[164:167], v[206:209], v[88:91]
	v_mfma_f32_16x16x32_bf16 v[76:79], v[156:159], v[214:217], v[76:79]
	v_mfma_f32_16x16x32_bf16 v[72:75], v[164:167], v[214:217], v[72:75]
	s_setprio 0
	s_setprio 1
	v_mfma_f32_16x16x32_bf16 v[116:119], v[168:171], v[186:189], v[116:119]
	v_mfma_f32_16x16x32_bf16 v[112:115], v[176:179], v[186:189], v[112:115]
	v_mfma_f32_16x16x32_bf16 v[100:103], v[168:171], v[194:197], v[100:103]
	v_mfma_f32_16x16x32_bf16 v[96:99], v[176:179], v[194:197], v[96:99]
	v_mfma_f32_16x16x32_bf16 v[84:87], v[168:171], v[202:205], v[84:87]
	v_mfma_f32_16x16x32_bf16 v[80:83], v[176:179], v[202:205], v[80:83]
	v_mfma_f32_16x16x32_bf16 v[68:71], v[168:171], v[210:213], v[68:71]
	v_mfma_f32_16x16x32_bf16 v[64:67], v[176:179], v[210:213], v[64:67]
	v_mfma_f32_16x16x32_bf16 v[116:119], v[172:175], v[190:193], v[116:119]
	v_mfma_f32_16x16x32_bf16 v[112:115], v[180:183], v[190:193], v[112:115]
	v_mfma_f32_16x16x32_bf16 v[100:103], v[172:175], v[198:201], v[100:103]
	v_mfma_f32_16x16x32_bf16 v[96:99], v[180:183], v[198:201], v[96:99]
	v_mfma_f32_16x16x32_bf16 v[84:87], v[172:175], v[206:209], v[84:87]
	v_mfma_f32_16x16x32_bf16 v[80:83], v[180:183], v[206:209], v[80:83]
	v_mfma_f32_16x16x32_bf16 v[68:71], v[172:175], v[214:217], v[68:71]
	v_mfma_f32_16x16x32_bf16 v[64:67], v[180:183], v[214:217], v[64:67]
	s_setprio 0
	s_barrier
	s_add_i32 s46, s52, s31
	v_lshl_add_u64 v[224:225], v[224:225], 0, s[36:37]
	s_mov_b32 m0, s46
	ds_read_b128 v[186:189], v153 offset:49152
	ds_read_b128 v[190:193], v153 offset:50176
	ds_read_b128 v[194:197], v153 offset:51200
	ds_read_b128 v[198:201], v153 offset:52224
	ds_read_b128 v[202:205], v153 offset:53248
	ds_read_b128 v[206:209], v153 offset:54272
	ds_read_b128 v[210:213], v153 offset:55296
	ds_read_b128 v[214:217], v153 offset:56320
	global_load_lds_dwordx4 v[224:225], off
	v_lshl_add_u64 v[224:225], v[226:227], 0, s[36:37]
	s_add_i32 m0, s46, 0x2000
	s_add_i32 s46, s53, s31
	global_load_lds_dwordx4 v[224:225], off
	v_lshl_add_u64 v[224:225], v[228:229], 0, s[36:37]
	s_mov_b32 m0, s46
	s_nop 0
	global_load_lds_dwordx4 v[224:225], off
	v_lshl_add_u64 v[224:225], v[230:231], 0, s[36:37]
	s_add_i32 m0, s46, 0x2000
	s_nop 0
	global_load_lds_dwordx4 v[224:225], off
	v_lshl_add_u64 v[224:225], v[232:233], 0, s[36:37]
	s_mov_b32 m0, s57
	s_nop 0
	global_load_lds_dwordx4 v[224:225], off
	v_lshl_add_u64 v[224:225], v[234:235], 0, s[36:37]
	s_mov_b32 m0, s58
	s_nop 0
	global_load_lds_dwordx4 v[224:225], off
	s_waitcnt vmcnt(8)
	s_waitcnt lgkmcnt(0)
	s_barrier
	s_setprio 1
	s_waitcnt lgkmcnt(0)
	v_mfma_f32_16x16x32_bf16 v[60:63], v[144:147], v[186:189], v[60:63]
	v_mfma_f32_16x16x32_bf16 v[56:59], v[160:163], v[186:189], v[56:59]
	v_mfma_f32_16x16x32_bf16 v[44:47], v[144:147], v[194:197], v[44:47]
	v_mfma_f32_16x16x32_bf16 v[40:43], v[160:163], v[194:197], v[40:43]
	v_mfma_f32_16x16x32_bf16 v[28:31], v[144:147], v[202:205], v[28:31]
	v_mfma_f32_16x16x32_bf16 v[24:27], v[160:163], v[202:205], v[24:27]
	v_mfma_f32_16x16x32_bf16 v[12:15], v[144:147], v[210:213], v[12:15]
	v_mfma_f32_16x16x32_bf16 v[8:11], v[160:163], v[210:213], v[8:11]
	v_mfma_f32_16x16x32_bf16 v[60:63], v[156:159], v[190:193], v[60:63]
	v_mfma_f32_16x16x32_bf16 v[56:59], v[164:167], v[190:193], v[56:59]
	v_mfma_f32_16x16x32_bf16 v[44:47], v[156:159], v[198:201], v[44:47]
	v_mfma_f32_16x16x32_bf16 v[40:43], v[164:167], v[198:201], v[40:43]
	v_mfma_f32_16x16x32_bf16 v[28:31], v[156:159], v[206:209], v[28:31]
	v_mfma_f32_16x16x32_bf16 v[24:27], v[164:167], v[206:209], v[24:27]
	v_mfma_f32_16x16x32_bf16 v[12:15], v[156:159], v[214:217], v[12:15]
	v_mfma_f32_16x16x32_bf16 v[8:11], v[164:167], v[214:217], v[8:11]
	s_setprio 0
	s_setprio 1
	v_mfma_f32_16x16x32_bf16 v[52:55], v[168:171], v[186:189], v[52:55]
	v_mfma_f32_16x16x32_bf16 v[48:51], v[176:179], v[186:189], v[48:51]
	v_mfma_f32_16x16x32_bf16 v[36:39], v[168:171], v[194:197], v[36:39]
	v_mfma_f32_16x16x32_bf16 v[32:35], v[176:179], v[194:197], v[32:35]
	v_mfma_f32_16x16x32_bf16 v[20:23], v[168:171], v[202:205], v[20:23]
	v_mfma_f32_16x16x32_bf16 v[16:19], v[176:179], v[202:205], v[16:19]
	v_mfma_f32_16x16x32_bf16 v[4:7], v[168:171], v[210:213], v[4:7]
	v_mfma_f32_16x16x32_bf16 v[0:3], v[176:179], v[210:213], v[0:3]
	v_mfma_f32_16x16x32_bf16 v[52:55], v[172:175], v[190:193], v[52:55]
	v_mfma_f32_16x16x32_bf16 v[48:51], v[180:183], v[190:193], v[48:51]
	v_mfma_f32_16x16x32_bf16 v[36:39], v[172:175], v[198:201], v[36:39]
	v_mfma_f32_16x16x32_bf16 v[32:35], v[180:183], v[198:201], v[32:35]
	v_mfma_f32_16x16x32_bf16 v[20:23], v[172:175], v[206:209], v[20:23]
	v_mfma_f32_16x16x32_bf16 v[16:19], v[180:183], v[206:209], v[16:19]
	v_mfma_f32_16x16x32_bf16 v[4:7], v[172:175], v[214:217], v[4:7]
	v_mfma_f32_16x16x32_bf16 v[0:3], v[180:183], v[214:217], v[0:3]
	s_setprio 0
	s_barrier
	s_add_u32 s4, s4, 0x100
	s_addc_u32 s5, s5, 0
	s_add_u32 s33, s33, 0x100
	s_addc_u32 s48, s48, 0
	s_cmp_ge_i32 s49, s59
	s_mov_b32 s46, s49
	s_cbranch_scc0 .LBB0_1112
	s_branch .LBB0_1113
